# GEMM K-loops: in the two-DMA load segments the scalar set-up and both LDS-DMA loads now precede all ds_reads
# speedup vs baseline: 1.0155x; 1.0030x over previous
.LBB0_94:
	s_add_u32 s24, s22, 0x4000
	s_addc_u32 s25, s23, 0
	s_cmp_eq_u32 s60, 60
	s_cselect_b32 s28, s2, s24
	s_cselect_b32 s29, s1, s25
	s_cselect_b32 s26, s15, s48
	s_cselect_b32 s27, s13, s49
	s_add_u32 s24, s28, 0x8000
	s_addc_u32 s25, s29, 0
	s_add_i32 m0, s21, 0xc000
	s_nop 0
	global_load_lds_dwordx4 v128, s[22:23]
	s_add_i32 m0, s21, 0xe000
	s_nop 0
	global_load_lds_dwordx4 v130, s[22:23]
	ds_read_b128 v[142:145], v160
	ds_read_b128 v[146:149], v160 offset:1024
	ds_read_b128 v[168:171], v160 offset:2048
	ds_read_b128 v[172:175], v160 offset:3072
	ds_read_b128 v[176:179], v161
	ds_read_b128 v[180:183], v161 offset:1024
	ds_read_b128 v[184:187], v161 offset:2048
	ds_read_b128 v[188:191], v161 offset:3072
	ds_read_b128 v[196:199], v162
	ds_read_b128 v[200:203], v162 offset:1024
	ds_read_b128 v[204:207], v162 offset:2048
	ds_read_b128 v[208:211], v162 offset:3072
	ds_read_b128 v[212:215], v162 offset:4096
	ds_read_b128 v[216:219], v162 offset:5120
	ds_read_b128 v[220:223], v162 offset:6144
	ds_read_b128 v[224:227], v162 offset:7168
	s_waitcnt vmcnt(8)
	s_waitcnt lgkmcnt(0)
	s_barrier
	s_setprio 1
	s_waitcnt lgkmcnt(0)
	v_mfma_f32_16x16x32_bf16 v[124:127], v[142:145], v[196:199], v[124:127]
	v_mfma_f32_16x16x32_bf16 v[120:123], v[168:171], v[196:199], v[120:123]
	v_mfma_f32_16x16x32_bf16 v[108:111], v[142:145], v[204:207], v[108:111]
	v_mfma_f32_16x16x32_bf16 v[104:107], v[168:171], v[204:207], v[104:107]
	v_mfma_f32_16x16x32_bf16 v[92:95], v[142:145], v[212:215], v[92:95]
	v_mfma_f32_16x16x32_bf16 v[88:91], v[168:171], v[212:215], v[88:91]
	v_mfma_f32_16x16x32_bf16 v[76:79], v[142:145], v[220:223], v[76:79]
	v_mfma_f32_16x16x32_bf16 v[72:75], v[168:171], v[220:223], v[72:75]
	v_mfma_f32_16x16x32_bf16 v[124:127], v[146:149], v[200:203], v[124:127]
	v_mfma_f32_16x16x32_bf16 v[120:123], v[172:175], v[200:203], v[120:123]
	v_mfma_f32_16x16x32_bf16 v[108:111], v[146:149], v[208:211], v[108:111]
	v_mfma_f32_16x16x32_bf16 v[104:107], v[172:175], v[208:211], v[104:107]
	v_mfma_f32_16x16x32_bf16 v[92:95], v[146:149], v[216:219], v[92:95]
	v_mfma_f32_16x16x32_bf16 v[88:91], v[172:175], v[216:219], v[88:91]
	v_mfma_f32_16x16x32_bf16 v[76:79], v[146:149], v[224:227], v[76:79]
	v_mfma_f32_16x16x32_bf16 v[72:75], v[172:175], v[224:227], v[72:75]
	s_setprio 0
	s_setprio 1
	v_mfma_f32_16x16x32_bf16 v[116:119], v[176:179], v[196:199], v[116:119]
	v_mfma_f32_16x16x32_bf16 v[112:115], v[184:187], v[196:199], v[112:115]
	v_mfma_f32_16x16x32_bf16 v[100:103], v[176:179], v[204:207], v[100:103]
	v_mfma_f32_16x16x32_bf16 v[96:99], v[184:187], v[204:207], v[96:99]
	v_mfma_f32_16x16x32_bf16 v[84:87], v[176:179], v[212:215], v[84:87]
	v_mfma_f32_16x16x32_bf16 v[80:83], v[184:187], v[212:215], v[80:83]
	v_mfma_f32_16x16x32_bf16 v[68:71], v[176:179], v[220:223], v[68:71]
	v_mfma_f32_16x16x32_bf16 v[64:67], v[184:187], v[220:223], v[64:67]
	v_mfma_f32_16x16x32_bf16 v[116:119], v[180:183], v[200:203], v[116:119]
	v_mfma_f32_16x16x32_bf16 v[112:115], v[188:191], v[200:203], v[112:115]
	v_mfma_f32_16x16x32_bf16 v[100:103], v[180:183], v[208:211], v[100:103]
	v_mfma_f32_16x16x32_bf16 v[96:99], v[188:191], v[208:211], v[96:99]
	v_mfma_f32_16x16x32_bf16 v[84:87], v[180:183], v[216:219], v[84:87]
	v_mfma_f32_16x16x32_bf16 v[80:83], v[188:191], v[216:219], v[80:83]
	v_mfma_f32_16x16x32_bf16 v[68:71], v[180:183], v[224:227], v[68:71]
	v_mfma_f32_16x16x32_bf16 v[64:67], v[188:191], v[224:227], v[64:67]
	s_setprio 0
	s_barrier
	s_add_i32 s61, s41, s3
	s_mov_b32 m0, s61
	s_nop 0
	global_load_lds_dwordx4 v128, s[26:27]
	s_add_i32 m0, s61, 0x2000
	s_add_u32 s62, s26, 0x4000
	s_addc_u32 s63, s27, 0
	s_add_i32 s61, s42, s3
	global_load_lds_dwordx4 v130, s[26:27]
	s_mov_b32 m0, s61
	s_nop 0
	global_load_lds_dwordx4 v128, s[62:63]
	s_add_i32 m0, s61, 0x2000
	s_nop 0
	global_load_lds_dwordx4 v130, s[62:63]
	s_mov_b32 m0, s21
	s_nop 0
	global_load_lds_dwordx4 v128, s[28:29]
	s_mov_b32 m0, s30
	s_nop 0
	global_load_lds_dwordx4 v130, s[28:29]
	ds_read_b128 v[196:199], v162 offset:16384
	ds_read_b128 v[200:203], v162 offset:17408
	ds_read_b128 v[204:207], v162 offset:18432
	ds_read_b128 v[208:211], v162 offset:19456
	ds_read_b128 v[212:215], v162 offset:20480
	ds_read_b128 v[216:219], v162 offset:21504
	ds_read_b128 v[220:223], v162 offset:22528
	ds_read_b128 v[224:227], v162 offset:23552
	s_waitcnt vmcnt(8)
	s_waitcnt lgkmcnt(0)
	s_barrier
	s_setprio 1
	s_waitcnt lgkmcnt(0)
	v_mfma_f32_16x16x32_bf16 v[60:63], v[142:145], v[196:199], v[60:63]
	v_mfma_f32_16x16x32_bf16 v[56:59], v[168:171], v[196:199], v[56:59]
	v_mfma_f32_16x16x32_bf16 v[44:47], v[142:145], v[204:207], v[44:47]
	v_mfma_f32_16x16x32_bf16 v[40:43], v[168:171], v[204:207], v[40:43]
	v_mfma_f32_16x16x32_bf16 v[28:31], v[142:145], v[212:215], v[28:31]
	v_mfma_f32_16x16x32_bf16 v[24:27], v[168:171], v[212:215], v[24:27]
	v_mfma_f32_16x16x32_bf16 v[12:15], v[142:145], v[220:223], v[12:15]
	v_mfma_f32_16x16x32_bf16 v[8:11], v[168:171], v[220:223], v[8:11]
	v_mfma_f32_16x16x32_bf16 v[60:63], v[146:149], v[200:203], v[60:63]
	v_mfma_f32_16x16x32_bf16 v[56:59], v[172:175], v[200:203], v[56:59]
	v_mfma_f32_16x16x32_bf16 v[44:47], v[146:149], v[208:211], v[44:47]
	v_mfma_f32_16x16x32_bf16 v[40:43], v[172:175], v[208:211], v[40:43]
	v_mfma_f32_16x16x32_bf16 v[28:31], v[146:149], v[216:219], v[28:31]
	v_mfma_f32_16x16x32_bf16 v[24:27], v[172:175], v[216:219], v[24:27]
	v_mfma_f32_16x16x32_bf16 v[12:15], v[146:149], v[224:227], v[12:15]
	v_mfma_f32_16x16x32_bf16 v[8:11], v[172:175], v[224:227], v[8:11]
	s_setprio 0
	s_setprio 1
	v_mfma_f32_16x16x32_bf16 v[52:55], v[176:179], v[196:199], v[52:55]
	v_mfma_f32_16x16x32_bf16 v[48:51], v[184:187], v[196:199], v[48:51]
	v_mfma_f32_16x16x32_bf16 v[36:39], v[176:179], v[204:207], v[36:39]
	v_mfma_f32_16x16x32_bf16 v[32:35], v[184:187], v[204:207], v[32:35]
	v_mfma_f32_16x16x32_bf16 v[20:23], v[176:179], v[212:215], v[20:23]
	v_mfma_f32_16x16x32_bf16 v[16:19], v[184:187], v[212:215], v[16:19]
	v_mfma_f32_16x16x32_bf16 v[4:7], v[176:179], v[220:223], v[4:7]
	v_mfma_f32_16x16x32_bf16 v[0:3], v[184:187], v[220:223], v[0:3]
	v_mfma_f32_16x16x32_bf16 v[52:55], v[180:183], v[200:203], v[52:55]
	v_mfma_f32_16x16x32_bf16 v[48:51], v[188:191], v[200:203], v[48:51]
	v_mfma_f32_16x16x32_bf16 v[36:39], v[180:183], v[208:211], v[36:39]
	v_mfma_f32_16x16x32_bf16 v[32:35], v[188:191], v[208:211], v[32:35]
	v_mfma_f32_16x16x32_bf16 v[20:23], v[180:183], v[216:219], v[20:23]
	v_mfma_f32_16x16x32_bf16 v[16:19], v[188:191], v[216:219], v[16:19]
	v_mfma_f32_16x16x32_bf16 v[4:7], v[180:183], v[224:227], v[4:7]
	v_mfma_f32_16x16x32_bf16 v[0:3], v[188:191], v[224:227], v[0:3]
	s_setprio 0
	s_barrier
	s_add_i32 s61, 0, 0x18000
	v_add_u32_e32 v132, s61, v135
	s_add_i32 s62, 0, 0x1c000
	s_add_u32 s28, s28, 0x4000
	s_addc_u32 s29, s29, 0
	s_mov_b32 m0, s31
	s_nop 0
	global_load_lds_dwordx4 v128, s[28:29]
	s_mov_b32 m0, s33
	s_nop 0
	global_load_lds_dwordx4 v130, s[28:29]
	ds_read_b128 v[142:145], v132
	ds_read_b128 v[146:149], v132 offset:1024
	ds_read_b128 v[168:171], v132 offset:2048
	ds_read_b128 v[172:175], v132 offset:3072
	v_add_u32_e32 v132, s62, v135
	ds_read_b128 v[176:179], v132
	ds_read_b128 v[180:183], v132 offset:1024
	ds_read_b128 v[184:187], v132 offset:2048
	ds_read_b128 v[188:191], v132 offset:3072
	ds_read_b128 v[196:199], v162 offset:32768
	ds_read_b128 v[200:203], v162 offset:33792
	ds_read_b128 v[204:207], v162 offset:34816
	ds_read_b128 v[208:211], v162 offset:35840
	ds_read_b128 v[212:215], v162 offset:36864
	ds_read_b128 v[216:219], v162 offset:37888
	ds_read_b128 v[220:223], v162 offset:38912
	ds_read_b128 v[224:227], v162 offset:39936
	s_waitcnt vmcnt(8)
	s_waitcnt lgkmcnt(0)
	s_barrier
	s_setprio 1
	s_waitcnt lgkmcnt(0)
	v_mfma_f32_16x16x32_bf16 v[124:127], v[142:145], v[196:199], v[124:127]
	v_mfma_f32_16x16x32_bf16 v[120:123], v[168:171], v[196:199], v[120:123]
	v_mfma_f32_16x16x32_bf16 v[108:111], v[142:145], v[204:207], v[108:111]
	v_mfma_f32_16x16x32_bf16 v[104:107], v[168:171], v[204:207], v[104:107]
	v_mfma_f32_16x16x32_bf16 v[92:95], v[142:145], v[212:215], v[92:95]
	v_mfma_f32_16x16x32_bf16 v[88:91], v[168:171], v[212:215], v[88:91]
	v_mfma_f32_16x16x32_bf16 v[76:79], v[142:145], v[220:223], v[76:79]
	v_mfma_f32_16x16x32_bf16 v[72:75], v[168:171], v[220:223], v[72:75]
	v_mfma_f32_16x16x32_bf16 v[124:127], v[146:149], v[200:203], v[124:127]
	v_mfma_f32_16x16x32_bf16 v[120:123], v[172:175], v[200:203], v[120:123]
	v_mfma_f32_16x16x32_bf16 v[108:111], v[146:149], v[208:211], v[108:111]
	v_mfma_f32_16x16x32_bf16 v[104:107], v[172:175], v[208:211], v[104:107]
	v_mfma_f32_16x16x32_bf16 v[92:95], v[146:149], v[216:219], v[92:95]
	v_mfma_f32_16x16x32_bf16 v[88:91], v[172:175], v[216:219], v[88:91]
	v_mfma_f32_16x16x32_bf16 v[76:79], v[146:149], v[224:227], v[76:79]
	v_mfma_f32_16x16x32_bf16 v[72:75], v[172:175], v[224:227], v[72:75]
	s_setprio 0
	s_setprio 1
	v_mfma_f32_16x16x32_bf16 v[116:119], v[176:179], v[196:199], v[116:119]
	v_mfma_f32_16x16x32_bf16 v[112:115], v[184:187], v[196:199], v[112:115]
	v_mfma_f32_16x16x32_bf16 v[100:103], v[176:179], v[204:207], v[100:103]
	v_mfma_f32_16x16x32_bf16 v[96:99], v[184:187], v[204:207], v[96:99]
	v_mfma_f32_16x16x32_bf16 v[84:87], v[176:179], v[212:215], v[84:87]
	v_mfma_f32_16x16x32_bf16 v[80:83], v[184:187], v[212:215], v[80:83]
	v_mfma_f32_16x16x32_bf16 v[68:71], v[176:179], v[220:223], v[68:71]
	v_mfma_f32_16x16x32_bf16 v[64:67], v[184:187], v[220:223], v[64:67]
	v_mfma_f32_16x16x32_bf16 v[116:119], v[180:183], v[200:203], v[116:119]
	v_mfma_f32_16x16x32_bf16 v[112:115], v[188:191], v[200:203], v[112:115]
	v_mfma_f32_16x16x32_bf16 v[100:103], v[180:183], v[208:211], v[100:103]
	v_mfma_f32_16x16x32_bf16 v[96:99], v[188:191], v[208:211], v[96:99]
	v_mfma_f32_16x16x32_bf16 v[84:87], v[180:183], v[216:219], v[84:87]
	v_mfma_f32_16x16x32_bf16 v[80:83], v[188:191], v[216:219], v[80:83]
	v_mfma_f32_16x16x32_bf16 v[68:71], v[180:183], v[224:227], v[68:71]
	v_mfma_f32_16x16x32_bf16 v[64:67], v[188:191], v[224:227], v[64:67]
	s_setprio 0
	s_barrier
	s_add_u32 s28, s26, 0x8000
	s_addc_u32 s29, s27, 0
	s_add_i32 s61, s61, s3
	s_mov_b32 m0, s61
	s_nop 0
	global_load_lds_dwordx4 v128, s[28:29]
	s_add_i32 m0, s61, 0x2000
	s_add_u32 s26, s26, 0xc000
	s_addc_u32 s27, s27, 0
	global_load_lds_dwordx4 v130, s[28:29]
	s_add_i32 s28, s62, s3
	s_mov_b32 m0, s28
	s_nop 0
	global_load_lds_dwordx4 v128, s[26:27]
	s_add_i32 m0, s28, 0x2000
	s_nop 0
	global_load_lds_dwordx4 v130, s[26:27]
	s_mov_b32 m0, s37
	s_nop 0
	global_load_lds_dwordx4 v128, s[24:25]
	s_mov_b32 m0, s38
	s_nop 0
	global_load_lds_dwordx4 v130, s[24:25]
	ds_read_b128 v[196:199], v162 offset:49152
	ds_read_b128 v[200:203], v162 offset:50176
	ds_read_b128 v[204:207], v162 offset:51200
	ds_read_b128 v[208:211], v162 offset:52224
	ds_read_b128 v[212:215], v162 offset:53248
	ds_read_b128 v[216:219], v162 offset:54272
	ds_read_b128 v[220:223], v162 offset:55296
	ds_read_b128 v[224:227], v162 offset:56320
	s_waitcnt vmcnt(8)
	s_waitcnt lgkmcnt(0)
	s_barrier
	s_setprio 1
	s_waitcnt lgkmcnt(0)
	v_mfma_f32_16x16x32_bf16 v[60:63], v[142:145], v[196:199], v[60:63]
	v_mfma_f32_16x16x32_bf16 v[56:59], v[168:171], v[196:199], v[56:59]
	v_mfma_f32_16x16x32_bf16 v[44:47], v[142:145], v[204:207], v[44:47]
	v_mfma_f32_16x16x32_bf16 v[40:43], v[168:171], v[204:207], v[40:43]
	v_mfma_f32_16x16x32_bf16 v[28:31], v[142:145], v[212:215], v[28:31]
	v_mfma_f32_16x16x32_bf16 v[24:27], v[168:171], v[212:215], v[24:27]
	v_mfma_f32_16x16x32_bf16 v[12:15], v[142:145], v[220:223], v[12:15]
	v_mfma_f32_16x16x32_bf16 v[8:11], v[168:171], v[220:223], v[8:11]
	v_mfma_f32_16x16x32_bf16 v[60:63], v[146:149], v[200:203], v[60:63]
	v_mfma_f32_16x16x32_bf16 v[56:59], v[172:175], v[200:203], v[56:59]
	v_mfma_f32_16x16x32_bf16 v[44:47], v[146:149], v[208:211], v[44:47]
	v_mfma_f32_16x16x32_bf16 v[40:43], v[172:175], v[208:211], v[40:43]
	v_mfma_f32_16x16x32_bf16 v[28:31], v[146:149], v[216:219], v[28:31]
	v_mfma_f32_16x16x32_bf16 v[24:27], v[172:175], v[216:219], v[24:27]
	v_mfma_f32_16x16x32_bf16 v[12:15], v[146:149], v[224:227], v[12:15]
	v_mfma_f32_16x16x32_bf16 v[8:11], v[172:175], v[224:227], v[8:11]
	s_setprio 0
	s_setprio 1
	v_mfma_f32_16x16x32_bf16 v[52:55], v[176:179], v[196:199], v[52:55]
	v_mfma_f32_16x16x32_bf16 v[48:51], v[184:187], v[196:199], v[48:51]
	v_mfma_f32_16x16x32_bf16 v[36:39], v[176:179], v[204:207], v[36:39]
	v_mfma_f32_16x16x32_bf16 v[32:35], v[184:187], v[204:207], v[32:35]
	v_mfma_f32_16x16x32_bf16 v[20:23], v[176:179], v[212:215], v[20:23]
	v_mfma_f32_16x16x32_bf16 v[16:19], v[184:187], v[212:215], v[16:19]
	v_mfma_f32_16x16x32_bf16 v[4:7], v[176:179], v[220:223], v[4:7]
	v_mfma_f32_16x16x32_bf16 v[0:3], v[184:187], v[220:223], v[0:3]
	v_mfma_f32_16x16x32_bf16 v[52:55], v[180:183], v[200:203], v[52:55]
	v_mfma_f32_16x16x32_bf16 v[48:51], v[188:191], v[200:203], v[48:51]
	v_mfma_f32_16x16x32_bf16 v[36:39], v[180:183], v[208:211], v[36:39]
	v_mfma_f32_16x16x32_bf16 v[32:35], v[188:191], v[208:211], v[32:35]
	v_mfma_f32_16x16x32_bf16 v[20:23], v[180:183], v[216:219], v[20:23]
	v_mfma_f32_16x16x32_bf16 v[16:19], v[188:191], v[216:219], v[16:19]
	v_mfma_f32_16x16x32_bf16 v[4:7], v[180:183], v[224:227], v[4:7]
	v_mfma_f32_16x16x32_bf16 v[0:3], v[188:191], v[224:227], v[0:3]
	s_setprio 0
	s_barrier
	s_add_i32 s60, s60, 2
	s_add_u32 s22, s22, 0x10000
	s_addc_u32 s23, s23, 0
	s_add_u32 s48, s48, 0x10000
	s_addc_u32 s49, s49, 0
	s_cmp_gt_u32 s60, 61
	s_cbranch_scc0 .LBB0_94
	s_and_b64 vcc, exec, s[10:11]
	s_cbranch_vccz .LBB0_97
	s_barrier

.LBB0_373:
	s_add_u32 s30, s28, 0x4000
	s_addc_u32 s31, s29, 0
	s_cmp_eq_u32 s49, 60
	s_cselect_b32 s36, s13, s30
	s_cselect_b32 s37, s2, s31
	s_cselect_b32 s34, s21, s27
	s_cselect_b32 s35, s19, s48
	s_add_u32 s30, s36, 0x8000
	s_addc_u32 s31, s37, 0
	s_add_i32 m0, s33, 0xc000
	s_nop 0
	global_load_lds_dwordx4 v144, s[28:29]
	s_add_i32 m0, s33, 0xe000
	s_nop 0
	global_load_lds_dwordx4 v146, s[28:29]
	ds_read_b128 v[128:131], v164
	ds_read_b128 v[132:135], v164 offset:1024
	ds_read_b128 v[136:139], v164 offset:2048
	ds_read_b128 v[140:143], v164 offset:3072
	ds_read_b128 v[154:157], v166
	ds_read_b128 v[170:173], v166 offset:1024
	ds_read_b128 v[174:177], v166 offset:2048
	ds_read_b128 v[178:181], v166 offset:3072
	ds_read_b128 v[182:185], v168
	ds_read_b128 v[186:189], v168 offset:1024
	ds_read_b128 v[190:193], v168 offset:2048
	ds_read_b128 v[196:199], v168 offset:3072
	ds_read_b128 v[200:203], v168 offset:4096
	ds_read_b128 v[204:207], v168 offset:5120
	ds_read_b128 v[208:211], v168 offset:6144
	ds_read_b128 v[212:215], v168 offset:7168
	s_waitcnt vmcnt(8)
	s_waitcnt lgkmcnt(0)
	s_barrier
	s_setprio 1
	s_waitcnt lgkmcnt(0)
	v_mfma_f32_16x16x32_bf16 v[124:127], v[128:131], v[182:185], v[124:127]
	v_mfma_f32_16x16x32_bf16 v[120:123], v[136:139], v[182:185], v[120:123]
	v_mfma_f32_16x16x32_bf16 v[108:111], v[128:131], v[190:193], v[108:111]
	v_mfma_f32_16x16x32_bf16 v[104:107], v[136:139], v[190:193], v[104:107]
	v_mfma_f32_16x16x32_bf16 v[92:95], v[128:131], v[200:203], v[92:95]
	v_mfma_f32_16x16x32_bf16 v[88:91], v[136:139], v[200:203], v[88:91]
	v_mfma_f32_16x16x32_bf16 v[76:79], v[128:131], v[208:211], v[76:79]
	v_mfma_f32_16x16x32_bf16 v[72:75], v[136:139], v[208:211], v[72:75]
	v_mfma_f32_16x16x32_bf16 v[124:127], v[132:135], v[186:189], v[124:127]
	v_mfma_f32_16x16x32_bf16 v[120:123], v[140:143], v[186:189], v[120:123]
	v_mfma_f32_16x16x32_bf16 v[108:111], v[132:135], v[196:199], v[108:111]
	v_mfma_f32_16x16x32_bf16 v[104:107], v[140:143], v[196:199], v[104:107]
	v_mfma_f32_16x16x32_bf16 v[92:95], v[132:135], v[204:207], v[92:95]
	v_mfma_f32_16x16x32_bf16 v[88:91], v[140:143], v[204:207], v[88:91]
	v_mfma_f32_16x16x32_bf16 v[76:79], v[132:135], v[212:215], v[76:79]
	v_mfma_f32_16x16x32_bf16 v[72:75], v[140:143], v[212:215], v[72:75]
	s_setprio 0
	s_setprio 1
	v_mfma_f32_16x16x32_bf16 v[116:119], v[154:157], v[182:185], v[116:119]
	v_mfma_f32_16x16x32_bf16 v[112:115], v[174:177], v[182:185], v[112:115]
	v_mfma_f32_16x16x32_bf16 v[100:103], v[154:157], v[190:193], v[100:103]
	v_mfma_f32_16x16x32_bf16 v[96:99], v[174:177], v[190:193], v[96:99]
	v_mfma_f32_16x16x32_bf16 v[84:87], v[154:157], v[200:203], v[84:87]
	v_mfma_f32_16x16x32_bf16 v[80:83], v[174:177], v[200:203], v[80:83]
	v_mfma_f32_16x16x32_bf16 v[68:71], v[154:157], v[208:211], v[68:71]
	v_mfma_f32_16x16x32_bf16 v[64:67], v[174:177], v[208:211], v[64:67]
	v_mfma_f32_16x16x32_bf16 v[116:119], v[170:173], v[186:189], v[116:119]
	v_mfma_f32_16x16x32_bf16 v[112:115], v[178:181], v[186:189], v[112:115]
	v_mfma_f32_16x16x32_bf16 v[100:103], v[170:173], v[196:199], v[100:103]
	v_mfma_f32_16x16x32_bf16 v[96:99], v[178:181], v[196:199], v[96:99]
	v_mfma_f32_16x16x32_bf16 v[84:87], v[170:173], v[204:207], v[84:87]
	v_mfma_f32_16x16x32_bf16 v[80:83], v[178:181], v[204:207], v[80:83]
	v_mfma_f32_16x16x32_bf16 v[68:71], v[170:173], v[212:215], v[68:71]
	v_mfma_f32_16x16x32_bf16 v[64:67], v[178:181], v[212:215], v[64:67]
	s_setprio 0
	s_barrier
	s_add_i32 s61, s57, s3
	s_mov_b32 m0, s61
	s_nop 0
	global_load_lds_dwordx4 v144, s[34:35]
	s_add_i32 m0, s61, 0x2000
	s_add_u32 s62, s34, 0x4000
	s_addc_u32 s63, s35, 0
	s_add_i32 s61, s60, s3
	global_load_lds_dwordx4 v146, s[34:35]
	s_mov_b32 m0, s61
	s_nop 0
	global_load_lds_dwordx4 v144, s[62:63]
	s_add_i32 m0, s61, 0x2000
	s_nop 0
	global_load_lds_dwordx4 v146, s[62:63]
	s_mov_b32 m0, s33
	s_nop 0
	global_load_lds_dwordx4 v144, s[36:37]
	s_mov_b32 m0, s38
	s_nop 0
	global_load_lds_dwordx4 v146, s[36:37]
	ds_read_b128 v[182:185], v168 offset:16384
	ds_read_b128 v[186:189], v168 offset:17408
	ds_read_b128 v[190:193], v168 offset:18432
	ds_read_b128 v[196:199], v168 offset:19456
	ds_read_b128 v[200:203], v168 offset:20480
	ds_read_b128 v[204:207], v168 offset:21504
	ds_read_b128 v[208:211], v168 offset:22528
	ds_read_b128 v[212:215], v168 offset:23552
	s_waitcnt vmcnt(8)
	s_waitcnt lgkmcnt(0)
	s_barrier
	s_setprio 1
	s_waitcnt lgkmcnt(0)
	v_mfma_f32_16x16x32_bf16 v[60:63], v[128:131], v[182:185], v[60:63]
	v_mfma_f32_16x16x32_bf16 v[56:59], v[136:139], v[182:185], v[56:59]
	v_mfma_f32_16x16x32_bf16 v[44:47], v[128:131], v[190:193], v[44:47]
	v_mfma_f32_16x16x32_bf16 v[40:43], v[136:139], v[190:193], v[40:43]
	v_mfma_f32_16x16x32_bf16 v[28:31], v[128:131], v[200:203], v[28:31]
	v_mfma_f32_16x16x32_bf16 v[24:27], v[136:139], v[200:203], v[24:27]
	v_mfma_f32_16x16x32_bf16 v[12:15], v[128:131], v[208:211], v[12:15]
	v_mfma_f32_16x16x32_bf16 v[8:11], v[136:139], v[208:211], v[8:11]
	v_mfma_f32_16x16x32_bf16 v[60:63], v[132:135], v[186:189], v[60:63]
	v_mfma_f32_16x16x32_bf16 v[56:59], v[140:143], v[186:189], v[56:59]
	v_mfma_f32_16x16x32_bf16 v[44:47], v[132:135], v[196:199], v[44:47]
	v_mfma_f32_16x16x32_bf16 v[40:43], v[140:143], v[196:199], v[40:43]
	v_mfma_f32_16x16x32_bf16 v[28:31], v[132:135], v[204:207], v[28:31]
	v_mfma_f32_16x16x32_bf16 v[24:27], v[140:143], v[204:207], v[24:27]
	v_mfma_f32_16x16x32_bf16 v[12:15], v[132:135], v[212:215], v[12:15]
	v_mfma_f32_16x16x32_bf16 v[8:11], v[140:143], v[212:215], v[8:11]
	s_setprio 0
	s_setprio 1
	v_mfma_f32_16x16x32_bf16 v[52:55], v[154:157], v[182:185], v[52:55]
	v_mfma_f32_16x16x32_bf16 v[48:51], v[174:177], v[182:185], v[48:51]
	v_mfma_f32_16x16x32_bf16 v[36:39], v[154:157], v[190:193], v[36:39]
	v_mfma_f32_16x16x32_bf16 v[32:35], v[174:177], v[190:193], v[32:35]
	v_mfma_f32_16x16x32_bf16 v[20:23], v[154:157], v[200:203], v[20:23]
	v_mfma_f32_16x16x32_bf16 v[16:19], v[174:177], v[200:203], v[16:19]
	v_mfma_f32_16x16x32_bf16 v[4:7], v[154:157], v[208:211], v[4:7]
	v_mfma_f32_16x16x32_bf16 v[0:3], v[174:177], v[208:211], v[0:3]
	v_mfma_f32_16x16x32_bf16 v[52:55], v[170:173], v[186:189], v[52:55]
	v_mfma_f32_16x16x32_bf16 v[48:51], v[178:181], v[186:189], v[48:51]
	v_mfma_f32_16x16x32_bf16 v[36:39], v[170:173], v[196:199], v[36:39]
	v_mfma_f32_16x16x32_bf16 v[32:35], v[178:181], v[196:199], v[32:35]
	v_mfma_f32_16x16x32_bf16 v[20:23], v[170:173], v[204:207], v[20:23]
	v_mfma_f32_16x16x32_bf16 v[16:19], v[178:181], v[204:207], v[16:19]
	v_mfma_f32_16x16x32_bf16 v[4:7], v[170:173], v[212:215], v[4:7]
	v_mfma_f32_16x16x32_bf16 v[0:3], v[178:181], v[212:215], v[0:3]
	s_setprio 0
	s_barrier
	s_add_i32 s61, 0, 0x18000
	s_add_i32 s62, 0, 0x1c000
	v_add_u32_e32 v140, s61, v162
	v_add_u32_e32 v148, s62, v162
	s_add_u32 s36, s36, 0x4000
	s_addc_u32 s37, s37, 0
	s_mov_b32 m0, s39
	s_nop 0
	global_load_lds_dwordx4 v144, s[36:37]
	s_mov_b32 m0, s40
	s_nop 0
	global_load_lds_dwordx4 v146, s[36:37]
	ds_read_b128 v[128:131], v140
	ds_read_b128 v[132:135], v140 offset:1024
	ds_read_b128 v[136:139], v140 offset:2048
	ds_read_b128 v[140:143], v140 offset:3072
	ds_read_b128 v[154:157], v148
	ds_read_b128 v[170:173], v148 offset:1024
	ds_read_b128 v[174:177], v148 offset:2048
	ds_read_b128 v[178:181], v148 offset:3072
	ds_read_b128 v[182:185], v168 offset:32768
	ds_read_b128 v[186:189], v168 offset:33792
	ds_read_b128 v[190:193], v168 offset:34816
	ds_read_b128 v[196:199], v168 offset:35840
	ds_read_b128 v[200:203], v168 offset:36864
	ds_read_b128 v[204:207], v168 offset:37888
	ds_read_b128 v[208:211], v168 offset:38912
	ds_read_b128 v[212:215], v168 offset:39936
	s_waitcnt vmcnt(8)
	s_waitcnt lgkmcnt(0)
	s_barrier
	s_setprio 1
	s_waitcnt lgkmcnt(0)
	v_mfma_f32_16x16x32_bf16 v[124:127], v[128:131], v[182:185], v[124:127]
	v_mfma_f32_16x16x32_bf16 v[120:123], v[136:139], v[182:185], v[120:123]
	v_mfma_f32_16x16x32_bf16 v[108:111], v[128:131], v[190:193], v[108:111]
	v_mfma_f32_16x16x32_bf16 v[104:107], v[136:139], v[190:193], v[104:107]
	v_mfma_f32_16x16x32_bf16 v[92:95], v[128:131], v[200:203], v[92:95]
	v_mfma_f32_16x16x32_bf16 v[88:91], v[136:139], v[200:203], v[88:91]
	v_mfma_f32_16x16x32_bf16 v[76:79], v[128:131], v[208:211], v[76:79]
	v_mfma_f32_16x16x32_bf16 v[72:75], v[136:139], v[208:211], v[72:75]
	v_mfma_f32_16x16x32_bf16 v[124:127], v[132:135], v[186:189], v[124:127]
	v_mfma_f32_16x16x32_bf16 v[120:123], v[140:143], v[186:189], v[120:123]
	v_mfma_f32_16x16x32_bf16 v[108:111], v[132:135], v[196:199], v[108:111]
	v_mfma_f32_16x16x32_bf16 v[104:107], v[140:143], v[196:199], v[104:107]
	v_mfma_f32_16x16x32_bf16 v[92:95], v[132:135], v[204:207], v[92:95]
	v_mfma_f32_16x16x32_bf16 v[88:91], v[140:143], v[204:207], v[88:91]
	v_mfma_f32_16x16x32_bf16 v[76:79], v[132:135], v[212:215], v[76:79]
	v_mfma_f32_16x16x32_bf16 v[72:75], v[140:143], v[212:215], v[72:75]
	s_setprio 0
	s_setprio 1
	v_mfma_f32_16x16x32_bf16 v[116:119], v[154:157], v[182:185], v[116:119]
	v_mfma_f32_16x16x32_bf16 v[112:115], v[174:177], v[182:185], v[112:115]
	v_mfma_f32_16x16x32_bf16 v[100:103], v[154:157], v[190:193], v[100:103]
	v_mfma_f32_16x16x32_bf16 v[96:99], v[174:177], v[190:193], v[96:99]
	v_mfma_f32_16x16x32_bf16 v[84:87], v[154:157], v[200:203], v[84:87]
	v_mfma_f32_16x16x32_bf16 v[80:83], v[174:177], v[200:203], v[80:83]
	v_mfma_f32_16x16x32_bf16 v[68:71], v[154:157], v[208:211], v[68:71]
	v_mfma_f32_16x16x32_bf16 v[64:67], v[174:177], v[208:211], v[64:67]
	v_mfma_f32_16x16x32_bf16 v[116:119], v[170:173], v[186:189], v[116:119]
	v_mfma_f32_16x16x32_bf16 v[112:115], v[178:181], v[186:189], v[112:115]
	v_mfma_f32_16x16x32_bf16 v[100:103], v[170:173], v[196:199], v[100:103]
	v_mfma_f32_16x16x32_bf16 v[96:99], v[178:181], v[196:199], v[96:99]
	v_mfma_f32_16x16x32_bf16 v[84:87], v[170:173], v[204:207], v[84:87]
	v_mfma_f32_16x16x32_bf16 v[80:83], v[178:181], v[204:207], v[80:83]
	v_mfma_f32_16x16x32_bf16 v[68:71], v[170:173], v[212:215], v[68:71]
	v_mfma_f32_16x16x32_bf16 v[64:67], v[178:181], v[212:215], v[64:67]
	s_setprio 0
	s_barrier
	s_add_u32 s36, s34, 0x8000
	s_addc_u32 s37, s35, 0
	s_add_i32 s61, s61, s3
	s_mov_b32 m0, s61
	s_nop 0
	global_load_lds_dwordx4 v144, s[36:37]
	s_add_i32 m0, s61, 0x2000
	s_add_u32 s34, s34, 0xc000
	s_addc_u32 s35, s35, 0
	global_load_lds_dwordx4 v146, s[36:37]
	s_add_i32 s36, s62, s3
	s_mov_b32 m0, s36
	s_nop 0
	global_load_lds_dwordx4 v144, s[34:35]
	s_add_i32 m0, s36, 0x2000
	s_nop 0
	global_load_lds_dwordx4 v146, s[34:35]
	s_mov_b32 m0, s46
	s_nop 0
	global_load_lds_dwordx4 v144, s[30:31]
	s_mov_b32 m0, s47
	s_nop 0
	global_load_lds_dwordx4 v146, s[30:31]
	ds_read_b128 v[182:185], v168 offset:49152
	ds_read_b128 v[186:189], v168 offset:50176
	ds_read_b128 v[190:193], v168 offset:51200
	ds_read_b128 v[196:199], v168 offset:52224
	ds_read_b128 v[200:203], v168 offset:53248
	ds_read_b128 v[204:207], v168 offset:54272
	ds_read_b128 v[208:211], v168 offset:55296
	ds_read_b128 v[212:215], v168 offset:56320
	s_waitcnt vmcnt(8)
	s_waitcnt lgkmcnt(0)
	s_barrier
	s_setprio 1
	s_waitcnt lgkmcnt(0)
	v_mfma_f32_16x16x32_bf16 v[60:63], v[128:131], v[182:185], v[60:63]
	v_mfma_f32_16x16x32_bf16 v[56:59], v[136:139], v[182:185], v[56:59]
	v_mfma_f32_16x16x32_bf16 v[44:47], v[128:131], v[190:193], v[44:47]
	v_mfma_f32_16x16x32_bf16 v[40:43], v[136:139], v[190:193], v[40:43]
	v_mfma_f32_16x16x32_bf16 v[28:31], v[128:131], v[200:203], v[28:31]
	v_mfma_f32_16x16x32_bf16 v[24:27], v[136:139], v[200:203], v[24:27]
	v_mfma_f32_16x16x32_bf16 v[12:15], v[128:131], v[208:211], v[12:15]
	v_mfma_f32_16x16x32_bf16 v[8:11], v[136:139], v[208:211], v[8:11]
	v_mfma_f32_16x16x32_bf16 v[60:63], v[132:135], v[186:189], v[60:63]
	v_mfma_f32_16x16x32_bf16 v[56:59], v[140:143], v[186:189], v[56:59]
	v_mfma_f32_16x16x32_bf16 v[44:47], v[132:135], v[196:199], v[44:47]
	v_mfma_f32_16x16x32_bf16 v[40:43], v[140:143], v[196:199], v[40:43]
	v_mfma_f32_16x16x32_bf16 v[28:31], v[132:135], v[204:207], v[28:31]
	v_mfma_f32_16x16x32_bf16 v[24:27], v[140:143], v[204:207], v[24:27]
	v_mfma_f32_16x16x32_bf16 v[12:15], v[132:135], v[212:215], v[12:15]
	v_mfma_f32_16x16x32_bf16 v[8:11], v[140:143], v[212:215], v[8:11]
	s_setprio 0
	s_setprio 1
	v_mfma_f32_16x16x32_bf16 v[52:55], v[154:157], v[182:185], v[52:55]
	v_mfma_f32_16x16x32_bf16 v[48:51], v[174:177], v[182:185], v[48:51]
	v_mfma_f32_16x16x32_bf16 v[36:39], v[154:157], v[190:193], v[36:39]
	v_mfma_f32_16x16x32_bf16 v[32:35], v[174:177], v[190:193], v[32:35]
	v_mfma_f32_16x16x32_bf16 v[20:23], v[154:157], v[200:203], v[20:23]
	v_mfma_f32_16x16x32_bf16 v[16:19], v[174:177], v[200:203], v[16:19]
	v_mfma_f32_16x16x32_bf16 v[4:7], v[154:157], v[208:211], v[4:7]
	v_mfma_f32_16x16x32_bf16 v[0:3], v[174:177], v[208:211], v[0:3]
	v_mfma_f32_16x16x32_bf16 v[52:55], v[170:173], v[186:189], v[52:55]
	v_mfma_f32_16x16x32_bf16 v[48:51], v[178:181], v[186:189], v[48:51]
	v_mfma_f32_16x16x32_bf16 v[36:39], v[170:173], v[196:199], v[36:39]
	v_mfma_f32_16x16x32_bf16 v[32:35], v[178:181], v[196:199], v[32:35]
	v_mfma_f32_16x16x32_bf16 v[20:23], v[170:173], v[204:207], v[20:23]
	v_mfma_f32_16x16x32_bf16 v[16:19], v[178:181], v[204:207], v[16:19]
	v_mfma_f32_16x16x32_bf16 v[4:7], v[170:173], v[212:215], v[4:7]
	v_mfma_f32_16x16x32_bf16 v[0:3], v[178:181], v[212:215], v[0:3]
	s_setprio 0
	s_barrier
	s_add_i32 s49, s49, 2
	s_add_u32 s28, s28, 0x10000
	s_addc_u32 s29, s29, 0
	s_add_u32 s27, s27, 0x10000
	s_addc_u32 s48, s48, 0
	s_cmp_gt_u32 s49, 61
	s_cbranch_scc0 .LBB0_373
	s_and_b64 vcc, exec, s[16:17]
	s_cbranch_vccz .LBB0_376
	s_barrier

.LBB0_469:
	s_add_u32 s28, s26, 0x4000
	s_addc_u32 s29, s27, 0
	s_cmp_eq_u32 s49, 60
	s_cselect_b32 s34, s2, s28
	s_cselect_b32 s35, s1, s29
	s_cselect_b32 s30, s19, s25
	s_cselect_b32 s31, s17, s48
	s_add_u32 s28, s34, 0x8000
	s_addc_u32 s29, s35, 0
	s_add_i32 m0, s33, 0xc000
	s_nop 0
	global_load_lds_dwordx4 v176, s[26:27]
	s_add_i32 m0, s33, 0xe000
	s_nop 0
	global_load_lds_dwordx4 v178, s[26:27]
	ds_read_b128 v[128:131], v197
	ds_read_b128 v[132:135], v197 offset:1024
	ds_read_b128 v[136:139], v197 offset:2048
	ds_read_b128 v[140:143], v197 offset:3072
	ds_read_b128 v[144:147], v198
	ds_read_b128 v[148:151], v198 offset:1024
	ds_read_b128 v[152:155], v198 offset:2048
	ds_read_b128 v[156:159], v198 offset:3072
	ds_read_b128 v[160:163], v199
	ds_read_b128 v[164:167], v199 offset:1024
	ds_read_b128 v[168:171], v199 offset:2048
	ds_read_b128 v[172:175], v199 offset:3072
	ds_read_b128 v[188:191], v199 offset:4096
	ds_read_b128 v[202:205], v199 offset:5120
	ds_read_b128 v[206:209], v199 offset:6144
	ds_read_b128 v[210:213], v199 offset:7168
	s_waitcnt vmcnt(8)
	s_waitcnt lgkmcnt(0)
	s_barrier
	s_setprio 1
	s_waitcnt lgkmcnt(0)
	v_mfma_f32_16x16x32_bf16 v[124:127], v[128:131], v[160:163], v[124:127]
	v_mfma_f32_16x16x32_bf16 v[120:123], v[136:139], v[160:163], v[120:123]
	v_mfma_f32_16x16x32_bf16 v[108:111], v[128:131], v[168:171], v[108:111]
	v_mfma_f32_16x16x32_bf16 v[104:107], v[136:139], v[168:171], v[104:107]
	v_mfma_f32_16x16x32_bf16 v[92:95], v[128:131], v[188:191], v[92:95]
	v_mfma_f32_16x16x32_bf16 v[88:91], v[136:139], v[188:191], v[88:91]
	v_mfma_f32_16x16x32_bf16 v[76:79], v[128:131], v[206:209], v[76:79]
	v_mfma_f32_16x16x32_bf16 v[72:75], v[136:139], v[206:209], v[72:75]
	v_mfma_f32_16x16x32_bf16 v[124:127], v[132:135], v[164:167], v[124:127]
	v_mfma_f32_16x16x32_bf16 v[120:123], v[140:143], v[164:167], v[120:123]
	v_mfma_f32_16x16x32_bf16 v[108:111], v[132:135], v[172:175], v[108:111]
	v_mfma_f32_16x16x32_bf16 v[104:107], v[140:143], v[172:175], v[104:107]
	v_mfma_f32_16x16x32_bf16 v[92:95], v[132:135], v[202:205], v[92:95]
	v_mfma_f32_16x16x32_bf16 v[88:91], v[140:143], v[202:205], v[88:91]
	v_mfma_f32_16x16x32_bf16 v[76:79], v[132:135], v[210:213], v[76:79]
	v_mfma_f32_16x16x32_bf16 v[72:75], v[140:143], v[210:213], v[72:75]
	s_setprio 0
	s_setprio 1
	v_mfma_f32_16x16x32_bf16 v[116:119], v[144:147], v[160:163], v[116:119]
	v_mfma_f32_16x16x32_bf16 v[112:115], v[152:155], v[160:163], v[112:115]
	v_mfma_f32_16x16x32_bf16 v[100:103], v[144:147], v[168:171], v[100:103]
	v_mfma_f32_16x16x32_bf16 v[96:99], v[152:155], v[168:171], v[96:99]
	v_mfma_f32_16x16x32_bf16 v[84:87], v[144:147], v[188:191], v[84:87]
	v_mfma_f32_16x16x32_bf16 v[80:83], v[152:155], v[188:191], v[80:83]
	v_mfma_f32_16x16x32_bf16 v[68:71], v[144:147], v[206:209], v[68:71]
	v_mfma_f32_16x16x32_bf16 v[64:67], v[152:155], v[206:209], v[64:67]
	v_mfma_f32_16x16x32_bf16 v[116:119], v[148:151], v[164:167], v[116:119]
	v_mfma_f32_16x16x32_bf16 v[112:115], v[156:159], v[164:167], v[112:115]
	v_mfma_f32_16x16x32_bf16 v[100:103], v[148:151], v[172:175], v[100:103]
	v_mfma_f32_16x16x32_bf16 v[96:99], v[156:159], v[172:175], v[96:99]
	v_mfma_f32_16x16x32_bf16 v[84:87], v[148:151], v[202:205], v[84:87]
	v_mfma_f32_16x16x32_bf16 v[80:83], v[156:159], v[202:205], v[80:83]
	v_mfma_f32_16x16x32_bf16 v[68:71], v[148:151], v[210:213], v[68:71]
	v_mfma_f32_16x16x32_bf16 v[64:67], v[156:159], v[210:213], v[64:67]
	s_setprio 0
	s_barrier
	s_add_i32 s50, s46, s3
	s_mov_b32 m0, s50
	s_nop 0
	global_load_lds_dwordx4 v176, s[30:31]
	s_add_i32 m0, s50, 0x2000
	s_add_u32 s50, s30, 0x4000
	s_addc_u32 s51, s31, 0
	s_add_i32 s52, s47, s3
	global_load_lds_dwordx4 v178, s[30:31]
	s_mov_b32 m0, s52
	s_nop 0
	global_load_lds_dwordx4 v176, s[50:51]
	s_add_i32 m0, s52, 0x2000
	s_nop 0
	global_load_lds_dwordx4 v178, s[50:51]
	s_mov_b32 m0, s33
	s_nop 0
	global_load_lds_dwordx4 v176, s[34:35]
	s_mov_b32 m0, s36
	s_nop 0
	global_load_lds_dwordx4 v178, s[34:35]
	ds_read_b128 v[160:163], v199 offset:16384
	ds_read_b128 v[164:167], v199 offset:17408
	ds_read_b128 v[168:171], v199 offset:18432
	ds_read_b128 v[172:175], v199 offset:19456
	ds_read_b128 v[188:191], v199 offset:20480
	ds_read_b128 v[202:205], v199 offset:21504
	ds_read_b128 v[206:209], v199 offset:22528
	ds_read_b128 v[210:213], v199 offset:23552
	s_waitcnt vmcnt(8)
	s_waitcnt lgkmcnt(0)
	s_barrier
	s_setprio 1
	s_waitcnt lgkmcnt(0)
	v_mfma_f32_16x16x32_bf16 v[60:63], v[128:131], v[160:163], v[60:63]
	v_mfma_f32_16x16x32_bf16 v[56:59], v[136:139], v[160:163], v[56:59]
	v_mfma_f32_16x16x32_bf16 v[44:47], v[128:131], v[168:171], v[44:47]
	v_mfma_f32_16x16x32_bf16 v[40:43], v[136:139], v[168:171], v[40:43]
	v_mfma_f32_16x16x32_bf16 v[28:31], v[128:131], v[188:191], v[28:31]
	v_mfma_f32_16x16x32_bf16 v[24:27], v[136:139], v[188:191], v[24:27]
	v_mfma_f32_16x16x32_bf16 v[12:15], v[128:131], v[206:209], v[12:15]
	v_mfma_f32_16x16x32_bf16 v[8:11], v[136:139], v[206:209], v[8:11]
	v_mfma_f32_16x16x32_bf16 v[60:63], v[132:135], v[164:167], v[60:63]
	v_mfma_f32_16x16x32_bf16 v[56:59], v[140:143], v[164:167], v[56:59]
	v_mfma_f32_16x16x32_bf16 v[44:47], v[132:135], v[172:175], v[44:47]
	v_mfma_f32_16x16x32_bf16 v[40:43], v[140:143], v[172:175], v[40:43]
	v_mfma_f32_16x16x32_bf16 v[28:31], v[132:135], v[202:205], v[28:31]
	v_mfma_f32_16x16x32_bf16 v[24:27], v[140:143], v[202:205], v[24:27]
	v_mfma_f32_16x16x32_bf16 v[12:15], v[132:135], v[210:213], v[12:15]
	v_mfma_f32_16x16x32_bf16 v[8:11], v[140:143], v[210:213], v[8:11]
	s_setprio 0
	s_setprio 1
	v_mfma_f32_16x16x32_bf16 v[52:55], v[144:147], v[160:163], v[52:55]
	v_mfma_f32_16x16x32_bf16 v[48:51], v[152:155], v[160:163], v[48:51]
	v_mfma_f32_16x16x32_bf16 v[36:39], v[144:147], v[168:171], v[36:39]
	v_mfma_f32_16x16x32_bf16 v[32:35], v[152:155], v[168:171], v[32:35]
	v_mfma_f32_16x16x32_bf16 v[20:23], v[144:147], v[188:191], v[20:23]
	v_mfma_f32_16x16x32_bf16 v[16:19], v[152:155], v[188:191], v[16:19]
	v_mfma_f32_16x16x32_bf16 v[4:7], v[144:147], v[206:209], v[4:7]
	v_mfma_f32_16x16x32_bf16 v[0:3], v[152:155], v[206:209], v[0:3]
	v_mfma_f32_16x16x32_bf16 v[52:55], v[148:151], v[164:167], v[52:55]
	v_mfma_f32_16x16x32_bf16 v[48:51], v[156:159], v[164:167], v[48:51]
	v_mfma_f32_16x16x32_bf16 v[36:39], v[148:151], v[172:175], v[36:39]
	v_mfma_f32_16x16x32_bf16 v[32:35], v[156:159], v[172:175], v[32:35]
	v_mfma_f32_16x16x32_bf16 v[20:23], v[148:151], v[202:205], v[20:23]
	v_mfma_f32_16x16x32_bf16 v[16:19], v[156:159], v[202:205], v[16:19]
	v_mfma_f32_16x16x32_bf16 v[4:7], v[148:151], v[210:213], v[4:7]
	v_mfma_f32_16x16x32_bf16 v[0:3], v[156:159], v[210:213], v[0:3]
	s_setprio 0
	s_barrier
	s_add_i32 s50, 0, 0x18000
	s_add_i32 s51, 0, 0x1c000
	v_add_u32_e32 v140, s50, v196
	v_add_u32_e32 v156, s51, v196
	s_add_u32 s34, s34, 0x4000
	s_addc_u32 s35, s35, 0
	s_mov_b32 m0, s37
	s_nop 0
	global_load_lds_dwordx4 v176, s[34:35]
	s_mov_b32 m0, s38
	s_nop 0
	global_load_lds_dwordx4 v178, s[34:35]
	ds_read_b128 v[128:131], v140
	ds_read_b128 v[132:135], v140 offset:1024
	ds_read_b128 v[136:139], v140 offset:2048
	ds_read_b128 v[140:143], v140 offset:3072
	ds_read_b128 v[144:147], v156
	ds_read_b128 v[148:151], v156 offset:1024
	ds_read_b128 v[152:155], v156 offset:2048
	ds_read_b128 v[156:159], v156 offset:3072
	ds_read_b128 v[160:163], v199 offset:32768
	ds_read_b128 v[164:167], v199 offset:33792
	ds_read_b128 v[168:171], v199 offset:34816
	ds_read_b128 v[172:175], v199 offset:35840
	ds_read_b128 v[188:191], v199 offset:36864
	ds_read_b128 v[202:205], v199 offset:37888
	ds_read_b128 v[206:209], v199 offset:38912
	ds_read_b128 v[210:213], v199 offset:39936
	s_waitcnt vmcnt(8)
	s_waitcnt lgkmcnt(0)
	s_barrier
	s_setprio 1
	s_waitcnt lgkmcnt(0)
	v_mfma_f32_16x16x32_bf16 v[124:127], v[128:131], v[160:163], v[124:127]
	v_mfma_f32_16x16x32_bf16 v[120:123], v[136:139], v[160:163], v[120:123]
	v_mfma_f32_16x16x32_bf16 v[108:111], v[128:131], v[168:171], v[108:111]
	v_mfma_f32_16x16x32_bf16 v[104:107], v[136:139], v[168:171], v[104:107]
	v_mfma_f32_16x16x32_bf16 v[92:95], v[128:131], v[188:191], v[92:95]
	v_mfma_f32_16x16x32_bf16 v[88:91], v[136:139], v[188:191], v[88:91]
	v_mfma_f32_16x16x32_bf16 v[76:79], v[128:131], v[206:209], v[76:79]
	v_mfma_f32_16x16x32_bf16 v[72:75], v[136:139], v[206:209], v[72:75]
	v_mfma_f32_16x16x32_bf16 v[124:127], v[132:135], v[164:167], v[124:127]
	v_mfma_f32_16x16x32_bf16 v[120:123], v[140:143], v[164:167], v[120:123]
	v_mfma_f32_16x16x32_bf16 v[108:111], v[132:135], v[172:175], v[108:111]
	v_mfma_f32_16x16x32_bf16 v[104:107], v[140:143], v[172:175], v[104:107]
	v_mfma_f32_16x16x32_bf16 v[92:95], v[132:135], v[202:205], v[92:95]
	v_mfma_f32_16x16x32_bf16 v[88:91], v[140:143], v[202:205], v[88:91]
	v_mfma_f32_16x16x32_bf16 v[76:79], v[132:135], v[210:213], v[76:79]
	v_mfma_f32_16x16x32_bf16 v[72:75], v[140:143], v[210:213], v[72:75]
	s_setprio 0
	s_setprio 1
	v_mfma_f32_16x16x32_bf16 v[116:119], v[144:147], v[160:163], v[116:119]
	v_mfma_f32_16x16x32_bf16 v[112:115], v[152:155], v[160:163], v[112:115]
	v_mfma_f32_16x16x32_bf16 v[100:103], v[144:147], v[168:171], v[100:103]
	v_mfma_f32_16x16x32_bf16 v[96:99], v[152:155], v[168:171], v[96:99]
	v_mfma_f32_16x16x32_bf16 v[84:87], v[144:147], v[188:191], v[84:87]
	v_mfma_f32_16x16x32_bf16 v[80:83], v[152:155], v[188:191], v[80:83]
	v_mfma_f32_16x16x32_bf16 v[68:71], v[144:147], v[206:209], v[68:71]
	v_mfma_f32_16x16x32_bf16 v[64:67], v[152:155], v[206:209], v[64:67]
	v_mfma_f32_16x16x32_bf16 v[116:119], v[148:151], v[164:167], v[116:119]
	v_mfma_f32_16x16x32_bf16 v[112:115], v[156:159], v[164:167], v[112:115]
	v_mfma_f32_16x16x32_bf16 v[100:103], v[148:151], v[172:175], v[100:103]
	v_mfma_f32_16x16x32_bf16 v[96:99], v[156:159], v[172:175], v[96:99]
	v_mfma_f32_16x16x32_bf16 v[84:87], v[148:151], v[202:205], v[84:87]
	v_mfma_f32_16x16x32_bf16 v[80:83], v[156:159], v[202:205], v[80:83]
	v_mfma_f32_16x16x32_bf16 v[68:71], v[148:151], v[210:213], v[68:71]
	v_mfma_f32_16x16x32_bf16 v[64:67], v[156:159], v[210:213], v[64:67]
	s_setprio 0
	s_barrier
	s_add_u32 s34, s30, 0x8000
	s_addc_u32 s35, s31, 0
	s_add_i32 s50, s50, s3
	s_mov_b32 m0, s50
	s_nop 0
	global_load_lds_dwordx4 v176, s[34:35]
	s_add_i32 m0, s50, 0x2000
	s_add_u32 s30, s30, 0xc000
	s_addc_u32 s31, s31, 0
	global_load_lds_dwordx4 v178, s[34:35]
	s_add_i32 s34, s51, s3
	s_mov_b32 m0, s34
	s_nop 0
	global_load_lds_dwordx4 v176, s[30:31]
	s_add_i32 m0, s34, 0x2000
	s_nop 0
	global_load_lds_dwordx4 v178, s[30:31]
	s_mov_b32 m0, s42
	s_nop 0
	global_load_lds_dwordx4 v176, s[28:29]
	s_mov_b32 m0, s43
	s_nop 0
	global_load_lds_dwordx4 v178, s[28:29]
	ds_read_b128 v[160:163], v199 offset:49152
	ds_read_b128 v[164:167], v199 offset:50176
	ds_read_b128 v[168:171], v199 offset:51200
	ds_read_b128 v[172:175], v199 offset:52224
	ds_read_b128 v[188:191], v199 offset:53248
	ds_read_b128 v[202:205], v199 offset:54272
	ds_read_b128 v[206:209], v199 offset:55296
	ds_read_b128 v[210:213], v199 offset:56320
	s_waitcnt vmcnt(8)
	s_waitcnt lgkmcnt(0)
	s_barrier
	s_setprio 1
	s_waitcnt lgkmcnt(0)
	v_mfma_f32_16x16x32_bf16 v[60:63], v[128:131], v[160:163], v[60:63]
	v_mfma_f32_16x16x32_bf16 v[56:59], v[136:139], v[160:163], v[56:59]
	v_mfma_f32_16x16x32_bf16 v[44:47], v[128:131], v[168:171], v[44:47]
	v_mfma_f32_16x16x32_bf16 v[40:43], v[136:139], v[168:171], v[40:43]
	v_mfma_f32_16x16x32_bf16 v[28:31], v[128:131], v[188:191], v[28:31]
	v_mfma_f32_16x16x32_bf16 v[24:27], v[136:139], v[188:191], v[24:27]
	v_mfma_f32_16x16x32_bf16 v[12:15], v[128:131], v[206:209], v[12:15]
	v_mfma_f32_16x16x32_bf16 v[8:11], v[136:139], v[206:209], v[8:11]
	v_mfma_f32_16x16x32_bf16 v[60:63], v[132:135], v[164:167], v[60:63]
	v_mfma_f32_16x16x32_bf16 v[56:59], v[140:143], v[164:167], v[56:59]
	v_mfma_f32_16x16x32_bf16 v[44:47], v[132:135], v[172:175], v[44:47]
	v_mfma_f32_16x16x32_bf16 v[40:43], v[140:143], v[172:175], v[40:43]
	v_mfma_f32_16x16x32_bf16 v[28:31], v[132:135], v[202:205], v[28:31]
	v_mfma_f32_16x16x32_bf16 v[24:27], v[140:143], v[202:205], v[24:27]
	v_mfma_f32_16x16x32_bf16 v[12:15], v[132:135], v[210:213], v[12:15]
	v_mfma_f32_16x16x32_bf16 v[8:11], v[140:143], v[210:213], v[8:11]
	s_setprio 0
	s_setprio 1
	v_mfma_f32_16x16x32_bf16 v[52:55], v[144:147], v[160:163], v[52:55]
	v_mfma_f32_16x16x32_bf16 v[48:51], v[152:155], v[160:163], v[48:51]
	v_mfma_f32_16x16x32_bf16 v[36:39], v[144:147], v[168:171], v[36:39]
	v_mfma_f32_16x16x32_bf16 v[32:35], v[152:155], v[168:171], v[32:35]
	v_mfma_f32_16x16x32_bf16 v[20:23], v[144:147], v[188:191], v[20:23]
	v_mfma_f32_16x16x32_bf16 v[16:19], v[152:155], v[188:191], v[16:19]
	v_mfma_f32_16x16x32_bf16 v[4:7], v[144:147], v[206:209], v[4:7]
	v_mfma_f32_16x16x32_bf16 v[0:3], v[152:155], v[206:209], v[0:3]
	v_mfma_f32_16x16x32_bf16 v[52:55], v[148:151], v[164:167], v[52:55]
	v_mfma_f32_16x16x32_bf16 v[48:51], v[156:159], v[164:167], v[48:51]
	v_mfma_f32_16x16x32_bf16 v[36:39], v[148:151], v[172:175], v[36:39]
	v_mfma_f32_16x16x32_bf16 v[32:35], v[156:159], v[172:175], v[32:35]
	v_mfma_f32_16x16x32_bf16 v[20:23], v[148:151], v[202:205], v[20:23]
	v_mfma_f32_16x16x32_bf16 v[16:19], v[156:159], v[202:205], v[16:19]
	v_mfma_f32_16x16x32_bf16 v[4:7], v[148:151], v[210:213], v[4:7]
	v_mfma_f32_16x16x32_bf16 v[0:3], v[156:159], v[210:213], v[0:3]
	s_setprio 0
	s_barrier
	s_add_i32 s49, s49, 2
	s_add_u32 s26, s26, 0x10000
	s_addc_u32 s27, s27, 0
	s_add_u32 s25, s25, 0x10000
	s_addc_u32 s48, s48, 0
	s_cmp_gt_u32 s49, 61
	s_cbranch_scc0 .LBB0_469
	s_and_b64 vcc, exec, s[12:13]
	s_cbranch_vccz .LBB0_472
	s_barrier

.LBB0_640:
	s_add_u32 s22, s20, 0x4000
	s_addc_u32 s23, s21, 0
	s_cmp_eq_u32 s51, 60
	s_cselect_b32 s26, s19, s22
	s_cselect_b32 s27, s11, s23
	s_cselect_b32 s24, s48, s49
	s_cselect_b32 s25, s13, s50
	s_add_u32 s22, s26, 0x8000
	s_addc_u32 s23, s27, 0
	s_add_i32 m0, s30, 0xc000
	s_nop 0
	global_load_lds_dwordx4 v160, s[20:21]
	s_add_i32 m0, s30, 0xe000
	s_nop 0
	global_load_lds_dwordx4 v162, s[20:21]
	ds_read_b128 v[56:59], v179
	ds_read_b128 v[60:63], v179 offset:1024
	ds_read_b128 v[64:67], v179 offset:2048
	ds_read_b128 v[68:71], v179 offset:3072
	ds_read_b128 v[144:147], v180
	ds_read_b128 v[148:151], v180 offset:1024
	ds_read_b128 v[152:155], v180 offset:2048
	ds_read_b128 v[156:159], v180 offset:3072
	ds_read_b128 v[172:175], v181
	ds_read_b128 v[182:185], v181 offset:1024
	ds_read_b128 v[186:189], v181 offset:2048
	ds_read_b128 v[190:193], v181 offset:3072
	ds_read_b128 v[196:199], v181 offset:4096
	ds_read_b128 v[200:203], v181 offset:5120
	ds_read_b128 v[204:207], v181 offset:6144
	ds_read_b128 v[208:211], v181 offset:7168
	s_waitcnt vmcnt(8)
	s_waitcnt lgkmcnt(0)
	s_barrier
	s_setprio 1
	s_waitcnt lgkmcnt(0)
	v_mfma_f32_16x16x32_bf16 v[140:143], v[56:59], v[172:175], v[140:143]
	v_mfma_f32_16x16x32_bf16 v[136:139], v[64:67], v[172:175], v[136:139]
	v_mfma_f32_16x16x32_bf16 v[124:127], v[56:59], v[186:189], v[124:127]
	v_mfma_f32_16x16x32_bf16 v[120:123], v[64:67], v[186:189], v[120:123]
	v_mfma_f32_16x16x32_bf16 v[108:111], v[56:59], v[196:199], v[108:111]
	v_mfma_f32_16x16x32_bf16 v[104:107], v[64:67], v[196:199], v[104:107]
	v_mfma_f32_16x16x32_bf16 v[92:95], v[56:59], v[204:207], v[92:95]
	v_mfma_f32_16x16x32_bf16 v[88:91], v[64:67], v[204:207], v[88:91]
	v_mfma_f32_16x16x32_bf16 v[140:143], v[60:63], v[182:185], v[140:143]
	v_mfma_f32_16x16x32_bf16 v[136:139], v[68:71], v[182:185], v[136:139]
	v_mfma_f32_16x16x32_bf16 v[124:127], v[60:63], v[190:193], v[124:127]
	v_mfma_f32_16x16x32_bf16 v[120:123], v[68:71], v[190:193], v[120:123]
	v_mfma_f32_16x16x32_bf16 v[108:111], v[60:63], v[200:203], v[108:111]
	v_mfma_f32_16x16x32_bf16 v[104:107], v[68:71], v[200:203], v[104:107]
	v_mfma_f32_16x16x32_bf16 v[92:95], v[60:63], v[208:211], v[92:95]
	v_mfma_f32_16x16x32_bf16 v[88:91], v[68:71], v[208:211], v[88:91]
	s_setprio 0
	s_setprio 1
	v_mfma_f32_16x16x32_bf16 v[132:135], v[144:147], v[172:175], v[132:135]
	v_mfma_f32_16x16x32_bf16 v[128:131], v[152:155], v[172:175], v[128:131]
	v_mfma_f32_16x16x32_bf16 v[116:119], v[144:147], v[186:189], v[116:119]
	v_mfma_f32_16x16x32_bf16 v[112:115], v[152:155], v[186:189], v[112:115]
	v_mfma_f32_16x16x32_bf16 v[100:103], v[144:147], v[196:199], v[100:103]
	v_mfma_f32_16x16x32_bf16 v[96:99], v[152:155], v[196:199], v[96:99]
	v_mfma_f32_16x16x32_bf16 v[84:87], v[144:147], v[204:207], v[84:87]
	v_mfma_f32_16x16x32_bf16 v[80:83], v[152:155], v[204:207], v[80:83]
	v_mfma_f32_16x16x32_bf16 v[132:135], v[148:151], v[182:185], v[132:135]
	v_mfma_f32_16x16x32_bf16 v[128:131], v[156:159], v[182:185], v[128:131]
	v_mfma_f32_16x16x32_bf16 v[116:119], v[148:151], v[190:193], v[116:119]
	v_mfma_f32_16x16x32_bf16 v[112:115], v[156:159], v[190:193], v[112:115]
	v_mfma_f32_16x16x32_bf16 v[100:103], v[148:151], v[200:203], v[100:103]
	v_mfma_f32_16x16x32_bf16 v[96:99], v[156:159], v[200:203], v[96:99]
	v_mfma_f32_16x16x32_bf16 v[84:87], v[148:151], v[208:211], v[84:87]
	v_mfma_f32_16x16x32_bf16 v[80:83], v[156:159], v[208:211], v[80:83]
	s_setprio 0
	s_barrier
	s_add_i32 s52, s46, s3
	s_mov_b32 m0, s52
	s_nop 0
	global_load_lds_dwordx4 v160, s[24:25]
	s_add_i32 m0, s52, 0x2000
	s_add_u32 s52, s24, 0x4000
	s_addc_u32 s53, s25, 0
	s_add_i32 s54, s47, s3
	global_load_lds_dwordx4 v162, s[24:25]
	s_mov_b32 m0, s54
	s_nop 0
	global_load_lds_dwordx4 v160, s[52:53]
	s_add_i32 m0, s54, 0x2000
	s_nop 0
	global_load_lds_dwordx4 v162, s[52:53]
	s_mov_b32 m0, s30
	s_nop 0
	global_load_lds_dwordx4 v160, s[26:27]
	s_mov_b32 m0, s31
	s_nop 0
	global_load_lds_dwordx4 v162, s[26:27]
	ds_read_b128 v[172:175], v181 offset:16384
	ds_read_b128 v[182:185], v181 offset:17408
	ds_read_b128 v[186:189], v181 offset:18432
	ds_read_b128 v[190:193], v181 offset:19456
	ds_read_b128 v[196:199], v181 offset:20480
	ds_read_b128 v[200:203], v181 offset:21504
	ds_read_b128 v[204:207], v181 offset:22528
	ds_read_b128 v[208:211], v181 offset:23552
	s_waitcnt vmcnt(8)
	s_waitcnt lgkmcnt(0)
	s_barrier
	s_setprio 1
	s_waitcnt lgkmcnt(0)
	v_mfma_f32_16x16x32_bf16 v[76:79], v[56:59], v[172:175], v[76:79]
	v_mfma_f32_16x16x32_bf16 v[72:75], v[64:67], v[172:175], v[72:75]
	v_mfma_f32_16x16x32_bf16 v[44:47], v[56:59], v[186:189], v[44:47]
	v_mfma_f32_16x16x32_bf16 v[40:43], v[64:67], v[186:189], v[40:43]
	v_mfma_f32_16x16x32_bf16 v[28:31], v[56:59], v[196:199], v[28:31]
	v_mfma_f32_16x16x32_bf16 v[24:27], v[64:67], v[196:199], v[24:27]
	v_mfma_f32_16x16x32_bf16 v[12:15], v[56:59], v[204:207], v[12:15]
	v_mfma_f32_16x16x32_bf16 v[8:11], v[64:67], v[204:207], v[8:11]
	v_mfma_f32_16x16x32_bf16 v[76:79], v[60:63], v[182:185], v[76:79]
	v_mfma_f32_16x16x32_bf16 v[72:75], v[68:71], v[182:185], v[72:75]
	v_mfma_f32_16x16x32_bf16 v[44:47], v[60:63], v[190:193], v[44:47]
	v_mfma_f32_16x16x32_bf16 v[40:43], v[68:71], v[190:193], v[40:43]
	v_mfma_f32_16x16x32_bf16 v[28:31], v[60:63], v[200:203], v[28:31]
	v_mfma_f32_16x16x32_bf16 v[24:27], v[68:71], v[200:203], v[24:27]
	v_mfma_f32_16x16x32_bf16 v[12:15], v[60:63], v[208:211], v[12:15]
	v_mfma_f32_16x16x32_bf16 v[8:11], v[68:71], v[208:211], v[8:11]
	s_setprio 0
	s_setprio 1
	v_mfma_f32_16x16x32_bf16 v[52:55], v[144:147], v[172:175], v[52:55]
	v_mfma_f32_16x16x32_bf16 v[48:51], v[152:155], v[172:175], v[48:51]
	v_mfma_f32_16x16x32_bf16 v[36:39], v[144:147], v[186:189], v[36:39]
	v_mfma_f32_16x16x32_bf16 v[32:35], v[152:155], v[186:189], v[32:35]
	v_mfma_f32_16x16x32_bf16 v[20:23], v[144:147], v[196:199], v[20:23]
	v_mfma_f32_16x16x32_bf16 v[16:19], v[152:155], v[196:199], v[16:19]
	v_mfma_f32_16x16x32_bf16 v[4:7], v[144:147], v[204:207], v[4:7]
	v_mfma_f32_16x16x32_bf16 v[0:3], v[152:155], v[204:207], v[0:3]
	v_mfma_f32_16x16x32_bf16 v[52:55], v[148:151], v[182:185], v[52:55]
	v_mfma_f32_16x16x32_bf16 v[48:51], v[156:159], v[182:185], v[48:51]
	v_mfma_f32_16x16x32_bf16 v[36:39], v[148:151], v[190:193], v[36:39]
	v_mfma_f32_16x16x32_bf16 v[32:35], v[156:159], v[190:193], v[32:35]
	v_mfma_f32_16x16x32_bf16 v[20:23], v[148:151], v[200:203], v[20:23]
	v_mfma_f32_16x16x32_bf16 v[16:19], v[156:159], v[200:203], v[16:19]
	v_mfma_f32_16x16x32_bf16 v[4:7], v[148:151], v[208:211], v[4:7]
	v_mfma_f32_16x16x32_bf16 v[0:3], v[156:159], v[208:211], v[0:3]
	s_setprio 0
	s_barrier
	s_add_i32 s52, 0, 0x18000
	s_add_i32 s53, 0, 0x1c000
	v_add_u32_e32 v68, s52, v178
	v_add_u32_e32 v156, s53, v178
	s_add_u32 s26, s26, 0x4000
	s_addc_u32 s27, s27, 0
	s_mov_b32 m0, s33
	s_nop 0
	global_load_lds_dwordx4 v160, s[26:27]
	s_mov_b32 m0, s34
	s_nop 0
	global_load_lds_dwordx4 v162, s[26:27]
	ds_read_b128 v[56:59], v68
	ds_read_b128 v[60:63], v68 offset:1024
	ds_read_b128 v[64:67], v68 offset:2048
	ds_read_b128 v[68:71], v68 offset:3072
	ds_read_b128 v[144:147], v156
	ds_read_b128 v[148:151], v156 offset:1024
	ds_read_b128 v[152:155], v156 offset:2048
	ds_read_b128 v[156:159], v156 offset:3072
	ds_read_b128 v[172:175], v181 offset:32768
	ds_read_b128 v[182:185], v181 offset:33792
	ds_read_b128 v[186:189], v181 offset:34816
	ds_read_b128 v[190:193], v181 offset:35840
	ds_read_b128 v[196:199], v181 offset:36864
	ds_read_b128 v[200:203], v181 offset:37888
	ds_read_b128 v[204:207], v181 offset:38912
	ds_read_b128 v[208:211], v181 offset:39936
	s_waitcnt vmcnt(8)
	s_waitcnt lgkmcnt(0)
	s_barrier
	s_setprio 1
	s_waitcnt lgkmcnt(0)
	v_mfma_f32_16x16x32_bf16 v[140:143], v[56:59], v[172:175], v[140:143]
	v_mfma_f32_16x16x32_bf16 v[136:139], v[64:67], v[172:175], v[136:139]
	v_mfma_f32_16x16x32_bf16 v[124:127], v[56:59], v[186:189], v[124:127]
	v_mfma_f32_16x16x32_bf16 v[120:123], v[64:67], v[186:189], v[120:123]
	v_mfma_f32_16x16x32_bf16 v[108:111], v[56:59], v[196:199], v[108:111]
	v_mfma_f32_16x16x32_bf16 v[104:107], v[64:67], v[196:199], v[104:107]
	v_mfma_f32_16x16x32_bf16 v[92:95], v[56:59], v[204:207], v[92:95]
	v_mfma_f32_16x16x32_bf16 v[88:91], v[64:67], v[204:207], v[88:91]
	v_mfma_f32_16x16x32_bf16 v[140:143], v[60:63], v[182:185], v[140:143]
	v_mfma_f32_16x16x32_bf16 v[136:139], v[68:71], v[182:185], v[136:139]
	v_mfma_f32_16x16x32_bf16 v[124:127], v[60:63], v[190:193], v[124:127]
	v_mfma_f32_16x16x32_bf16 v[120:123], v[68:71], v[190:193], v[120:123]
	v_mfma_f32_16x16x32_bf16 v[108:111], v[60:63], v[200:203], v[108:111]
	v_mfma_f32_16x16x32_bf16 v[104:107], v[68:71], v[200:203], v[104:107]
	v_mfma_f32_16x16x32_bf16 v[92:95], v[60:63], v[208:211], v[92:95]
	v_mfma_f32_16x16x32_bf16 v[88:91], v[68:71], v[208:211], v[88:91]
	s_setprio 0
	s_setprio 1
	v_mfma_f32_16x16x32_bf16 v[132:135], v[144:147], v[172:175], v[132:135]
	v_mfma_f32_16x16x32_bf16 v[128:131], v[152:155], v[172:175], v[128:131]
	v_mfma_f32_16x16x32_bf16 v[116:119], v[144:147], v[186:189], v[116:119]
	v_mfma_f32_16x16x32_bf16 v[112:115], v[152:155], v[186:189], v[112:115]
	v_mfma_f32_16x16x32_bf16 v[100:103], v[144:147], v[196:199], v[100:103]
	v_mfma_f32_16x16x32_bf16 v[96:99], v[152:155], v[196:199], v[96:99]
	v_mfma_f32_16x16x32_bf16 v[84:87], v[144:147], v[204:207], v[84:87]
	v_mfma_f32_16x16x32_bf16 v[80:83], v[152:155], v[204:207], v[80:83]
	v_mfma_f32_16x16x32_bf16 v[132:135], v[148:151], v[182:185], v[132:135]
	v_mfma_f32_16x16x32_bf16 v[128:131], v[156:159], v[182:185], v[128:131]
	v_mfma_f32_16x16x32_bf16 v[116:119], v[148:151], v[190:193], v[116:119]
	v_mfma_f32_16x16x32_bf16 v[112:115], v[156:159], v[190:193], v[112:115]
	v_mfma_f32_16x16x32_bf16 v[100:103], v[148:151], v[200:203], v[100:103]
	v_mfma_f32_16x16x32_bf16 v[96:99], v[156:159], v[200:203], v[96:99]
	v_mfma_f32_16x16x32_bf16 v[84:87], v[148:151], v[208:211], v[84:87]
	v_mfma_f32_16x16x32_bf16 v[80:83], v[156:159], v[208:211], v[80:83]
	s_setprio 0
	s_barrier
	s_add_u32 s26, s24, 0x8000
	s_addc_u32 s27, s25, 0
	s_add_i32 s52, s52, s3
	s_mov_b32 m0, s52
	s_nop 0
	global_load_lds_dwordx4 v160, s[26:27]
	s_add_i32 m0, s52, 0x2000
	s_add_u32 s24, s24, 0xc000
	s_addc_u32 s25, s25, 0
	global_load_lds_dwordx4 v162, s[26:27]
	s_add_i32 s26, s53, s3
	s_mov_b32 m0, s26
	s_nop 0
	global_load_lds_dwordx4 v160, s[24:25]
	s_add_i32 m0, s26, 0x2000
	s_nop 0
	global_load_lds_dwordx4 v162, s[24:25]
	s_mov_b32 m0, s39
	s_nop 0
	global_load_lds_dwordx4 v160, s[22:23]
	s_mov_b32 m0, s40
	s_nop 0
	global_load_lds_dwordx4 v162, s[22:23]
	ds_read_b128 v[172:175], v181 offset:49152
	ds_read_b128 v[182:185], v181 offset:50176
	ds_read_b128 v[186:189], v181 offset:51200
	ds_read_b128 v[190:193], v181 offset:52224
	ds_read_b128 v[196:199], v181 offset:53248
	ds_read_b128 v[200:203], v181 offset:54272
	ds_read_b128 v[204:207], v181 offset:55296
	ds_read_b128 v[208:211], v181 offset:56320
	s_waitcnt vmcnt(8)
	s_waitcnt lgkmcnt(0)
	s_barrier
	s_setprio 1
	s_waitcnt lgkmcnt(0)
	v_mfma_f32_16x16x32_bf16 v[76:79], v[56:59], v[172:175], v[76:79]
	v_mfma_f32_16x16x32_bf16 v[72:75], v[64:67], v[172:175], v[72:75]
	v_mfma_f32_16x16x32_bf16 v[44:47], v[56:59], v[186:189], v[44:47]
	v_mfma_f32_16x16x32_bf16 v[40:43], v[64:67], v[186:189], v[40:43]
	v_mfma_f32_16x16x32_bf16 v[28:31], v[56:59], v[196:199], v[28:31]
	v_mfma_f32_16x16x32_bf16 v[24:27], v[64:67], v[196:199], v[24:27]
	v_mfma_f32_16x16x32_bf16 v[12:15], v[56:59], v[204:207], v[12:15]
	v_mfma_f32_16x16x32_bf16 v[8:11], v[64:67], v[204:207], v[8:11]
	v_mfma_f32_16x16x32_bf16 v[76:79], v[60:63], v[182:185], v[76:79]
	v_mfma_f32_16x16x32_bf16 v[72:75], v[68:71], v[182:185], v[72:75]
	v_mfma_f32_16x16x32_bf16 v[44:47], v[60:63], v[190:193], v[44:47]
	v_mfma_f32_16x16x32_bf16 v[40:43], v[68:71], v[190:193], v[40:43]
	v_mfma_f32_16x16x32_bf16 v[28:31], v[60:63], v[200:203], v[28:31]
	v_mfma_f32_16x16x32_bf16 v[24:27], v[68:71], v[200:203], v[24:27]
	v_mfma_f32_16x16x32_bf16 v[12:15], v[60:63], v[208:211], v[12:15]
	v_mfma_f32_16x16x32_bf16 v[8:11], v[68:71], v[208:211], v[8:11]
	s_setprio 0
	s_setprio 1
	v_mfma_f32_16x16x32_bf16 v[52:55], v[144:147], v[172:175], v[52:55]
	v_mfma_f32_16x16x32_bf16 v[48:51], v[152:155], v[172:175], v[48:51]
	v_mfma_f32_16x16x32_bf16 v[36:39], v[144:147], v[186:189], v[36:39]
	v_mfma_f32_16x16x32_bf16 v[32:35], v[152:155], v[186:189], v[32:35]
	v_mfma_f32_16x16x32_bf16 v[20:23], v[144:147], v[196:199], v[20:23]
	v_mfma_f32_16x16x32_bf16 v[16:19], v[152:155], v[196:199], v[16:19]
	v_mfma_f32_16x16x32_bf16 v[4:7], v[144:147], v[204:207], v[4:7]
	v_mfma_f32_16x16x32_bf16 v[0:3], v[152:155], v[204:207], v[0:3]
	v_mfma_f32_16x16x32_bf16 v[52:55], v[148:151], v[182:185], v[52:55]
	v_mfma_f32_16x16x32_bf16 v[48:51], v[156:159], v[182:185], v[48:51]
	v_mfma_f32_16x16x32_bf16 v[36:39], v[148:151], v[190:193], v[36:39]
	v_mfma_f32_16x16x32_bf16 v[32:35], v[156:159], v[190:193], v[32:35]
	v_mfma_f32_16x16x32_bf16 v[20:23], v[148:151], v[200:203], v[20:23]
	v_mfma_f32_16x16x32_bf16 v[16:19], v[156:159], v[200:203], v[16:19]
	v_mfma_f32_16x16x32_bf16 v[4:7], v[148:151], v[208:211], v[4:7]
	v_mfma_f32_16x16x32_bf16 v[0:3], v[156:159], v[208:211], v[0:3]
	s_setprio 0
	s_barrier
	s_add_i32 s51, s51, 2
	s_add_u32 s20, s20, 0x10000
	s_addc_u32 s21, s21, 0
	s_add_u32 s49, s49, 0x10000
	s_addc_u32 s50, s50, 0
	s_cmp_gt_u32 s51, 61
	s_cbranch_scc0 .LBB0_640
	s_and_b64 vcc, exec, s[6:7]
	s_cbranch_vccz .LBB0_643
	s_barrier

.LBB0_716:
	s_add_u32 s20, s18, 0x4000
	s_addc_u32 s21, s19, 0
	s_cmp_eq_u32 s48, 60
	s_cselect_b32 s24, s44, s20
	s_cselect_b32 s25, s9, s21
	s_cselect_b32 s22, s45, s46
	s_cselect_b32 s23, s11, s47
	s_add_u32 s20, s24, 0x8000
	s_addc_u32 s21, s25, 0
	s_add_i32 m0, s28, 0xc000
	s_nop 0
	global_load_lds_dwordx4 v128, s[18:19]
	s_add_i32 m0, s28, 0xe000
	s_nop 0
	global_load_lds_dwordx4 v130, s[18:19]
	ds_read_b128 v[138:141], v145
	ds_read_b128 v[148:151], v145 offset:1024
	ds_read_b128 v[152:155], v145 offset:2048
	ds_read_b128 v[156:159], v145 offset:3072
	ds_read_b128 v[160:163], v146
	ds_read_b128 v[164:167], v146 offset:1024
	ds_read_b128 v[168:171], v146 offset:2048
	ds_read_b128 v[172:175], v146 offset:3072
	ds_read_b128 v[176:179], v147
	ds_read_b128 v[180:183], v147 offset:1024
	ds_read_b128 v[184:187], v147 offset:2048
	ds_read_b128 v[188:191], v147 offset:3072
	ds_read_b128 v[192:195], v147 offset:4096
	ds_read_b128 v[196:199], v147 offset:5120
	ds_read_b128 v[200:203], v147 offset:6144
	ds_read_b128 v[204:207], v147 offset:7168
	s_waitcnt vmcnt(8)
	s_waitcnt lgkmcnt(0)
	s_barrier
	s_setprio 1
	s_waitcnt lgkmcnt(0)
	v_mfma_f32_16x16x32_bf16 v[124:127], v[138:141], v[176:179], v[124:127]
	v_mfma_f32_16x16x32_bf16 v[120:123], v[152:155], v[176:179], v[120:123]
	v_mfma_f32_16x16x32_bf16 v[116:119], v[138:141], v[184:187], v[116:119]
	v_mfma_f32_16x16x32_bf16 v[104:107], v[152:155], v[184:187], v[104:107]
	v_mfma_f32_16x16x32_bf16 v[92:95], v[138:141], v[192:195], v[92:95]
	v_mfma_f32_16x16x32_bf16 v[88:91], v[152:155], v[192:195], v[88:91]
	v_mfma_f32_16x16x32_bf16 v[84:87], v[138:141], v[200:203], v[84:87]
	v_mfma_f32_16x16x32_bf16 v[72:75], v[152:155], v[200:203], v[72:75]
	v_mfma_f32_16x16x32_bf16 v[124:127], v[148:151], v[180:183], v[124:127]
	v_mfma_f32_16x16x32_bf16 v[120:123], v[156:159], v[180:183], v[120:123]
	v_mfma_f32_16x16x32_bf16 v[116:119], v[148:151], v[188:191], v[116:119]
	v_mfma_f32_16x16x32_bf16 v[104:107], v[156:159], v[188:191], v[104:107]
	v_mfma_f32_16x16x32_bf16 v[92:95], v[148:151], v[196:199], v[92:95]
	v_mfma_f32_16x16x32_bf16 v[88:91], v[156:159], v[196:199], v[88:91]
	v_mfma_f32_16x16x32_bf16 v[84:87], v[148:151], v[204:207], v[84:87]
	v_mfma_f32_16x16x32_bf16 v[72:75], v[156:159], v[204:207], v[72:75]
	s_setprio 0
	s_setprio 1
	v_mfma_f32_16x16x32_bf16 v[112:115], v[160:163], v[176:179], v[112:115]
	v_mfma_f32_16x16x32_bf16 v[108:111], v[168:171], v[176:179], v[108:111]
	v_mfma_f32_16x16x32_bf16 v[100:103], v[160:163], v[184:187], v[100:103]
	v_mfma_f32_16x16x32_bf16 v[96:99], v[168:171], v[184:187], v[96:99]
	v_mfma_f32_16x16x32_bf16 v[80:83], v[160:163], v[192:195], v[80:83]
	v_mfma_f32_16x16x32_bf16 v[76:79], v[168:171], v[192:195], v[76:79]
	v_mfma_f32_16x16x32_bf16 v[68:71], v[160:163], v[200:203], v[68:71]
	v_mfma_f32_16x16x32_bf16 v[64:67], v[168:171], v[200:203], v[64:67]
	v_mfma_f32_16x16x32_bf16 v[112:115], v[164:167], v[180:183], v[112:115]
	v_mfma_f32_16x16x32_bf16 v[108:111], v[172:175], v[180:183], v[108:111]
	v_mfma_f32_16x16x32_bf16 v[100:103], v[164:167], v[188:191], v[100:103]
	v_mfma_f32_16x16x32_bf16 v[96:99], v[172:175], v[188:191], v[96:99]
	v_mfma_f32_16x16x32_bf16 v[80:83], v[164:167], v[196:199], v[80:83]
	v_mfma_f32_16x16x32_bf16 v[76:79], v[172:175], v[196:199], v[76:79]
	v_mfma_f32_16x16x32_bf16 v[68:71], v[164:167], v[204:207], v[68:71]
	v_mfma_f32_16x16x32_bf16 v[64:67], v[172:175], v[204:207], v[64:67]
	s_setprio 0
	s_barrier
	s_add_i32 s49, s42, s3
	s_mov_b32 m0, s49
	s_nop 0
	global_load_lds_dwordx4 v128, s[22:23]
	s_add_i32 m0, s49, 0x2000
	s_add_u32 s50, s22, 0x4000
	s_addc_u32 s51, s23, 0
	s_add_i32 s49, s43, s3
	global_load_lds_dwordx4 v130, s[22:23]
	s_mov_b32 m0, s49
	s_nop 0
	global_load_lds_dwordx4 v128, s[50:51]
	s_add_i32 m0, s49, 0x2000
	s_nop 0
	global_load_lds_dwordx4 v130, s[50:51]
	s_mov_b32 m0, s28
	s_nop 0
	global_load_lds_dwordx4 v128, s[24:25]
	s_mov_b32 m0, s29
	s_nop 0
	global_load_lds_dwordx4 v130, s[24:25]
	ds_read_b128 v[176:179], v147 offset:16384
	ds_read_b128 v[180:183], v147 offset:17408
	ds_read_b128 v[184:187], v147 offset:18432
	ds_read_b128 v[188:191], v147 offset:19456
	ds_read_b128 v[192:195], v147 offset:20480
	ds_read_b128 v[196:199], v147 offset:21504
	ds_read_b128 v[200:203], v147 offset:22528
	ds_read_b128 v[204:207], v147 offset:23552
	s_waitcnt vmcnt(8)
	s_waitcnt lgkmcnt(0)
	s_barrier
	s_setprio 1
	s_waitcnt lgkmcnt(0)
	v_mfma_f32_16x16x32_bf16 v[60:63], v[138:141], v[176:179], v[60:63]
	v_mfma_f32_16x16x32_bf16 v[56:59], v[152:155], v[176:179], v[56:59]
	v_mfma_f32_16x16x32_bf16 v[48:51], v[138:141], v[184:187], v[48:51]
	v_mfma_f32_16x16x32_bf16 v[40:43], v[152:155], v[184:187], v[40:43]
	v_mfma_f32_16x16x32_bf16 v[28:31], v[138:141], v[192:195], v[28:31]
	v_mfma_f32_16x16x32_bf16 v[24:27], v[152:155], v[192:195], v[24:27]
	v_mfma_f32_16x16x32_bf16 v[16:19], v[138:141], v[200:203], v[16:19]
	v_mfma_f32_16x16x32_bf16 v[8:11], v[152:155], v[200:203], v[8:11]
	v_mfma_f32_16x16x32_bf16 v[60:63], v[148:151], v[180:183], v[60:63]
	v_mfma_f32_16x16x32_bf16 v[56:59], v[156:159], v[180:183], v[56:59]
	v_mfma_f32_16x16x32_bf16 v[48:51], v[148:151], v[188:191], v[48:51]
	v_mfma_f32_16x16x32_bf16 v[40:43], v[156:159], v[188:191], v[40:43]
	v_mfma_f32_16x16x32_bf16 v[28:31], v[148:151], v[196:199], v[28:31]
	v_mfma_f32_16x16x32_bf16 v[24:27], v[156:159], v[196:199], v[24:27]
	v_mfma_f32_16x16x32_bf16 v[16:19], v[148:151], v[204:207], v[16:19]
	v_mfma_f32_16x16x32_bf16 v[8:11], v[156:159], v[204:207], v[8:11]
	s_setprio 0
	s_setprio 1
	v_mfma_f32_16x16x32_bf16 v[52:55], v[160:163], v[176:179], v[52:55]
	v_mfma_f32_16x16x32_bf16 v[44:47], v[168:171], v[176:179], v[44:47]
	v_mfma_f32_16x16x32_bf16 v[36:39], v[160:163], v[184:187], v[36:39]
	v_mfma_f32_16x16x32_bf16 v[32:35], v[168:171], v[184:187], v[32:35]
	v_mfma_f32_16x16x32_bf16 v[20:23], v[160:163], v[192:195], v[20:23]
	v_mfma_f32_16x16x32_bf16 v[12:15], v[168:171], v[192:195], v[12:15]
	v_mfma_f32_16x16x32_bf16 v[4:7], v[160:163], v[200:203], v[4:7]
	v_mfma_f32_16x16x32_bf16 v[0:3], v[168:171], v[200:203], v[0:3]
	v_mfma_f32_16x16x32_bf16 v[52:55], v[164:167], v[180:183], v[52:55]
	v_mfma_f32_16x16x32_bf16 v[44:47], v[172:175], v[180:183], v[44:47]
	v_mfma_f32_16x16x32_bf16 v[36:39], v[164:167], v[188:191], v[36:39]
	v_mfma_f32_16x16x32_bf16 v[32:35], v[172:175], v[188:191], v[32:35]
	v_mfma_f32_16x16x32_bf16 v[20:23], v[164:167], v[196:199], v[20:23]
	v_mfma_f32_16x16x32_bf16 v[12:15], v[172:175], v[196:199], v[12:15]
	v_mfma_f32_16x16x32_bf16 v[4:7], v[164:167], v[204:207], v[4:7]
	v_mfma_f32_16x16x32_bf16 v[0:3], v[172:175], v[204:207], v[0:3]
	s_setprio 0
	s_barrier
	s_add_i32 s49, 0, 0x18000
	v_add_u32_e32 v132, s49, v144
	s_add_i32 s50, 0, 0x1c000
	s_add_u32 s24, s24, 0x4000
	s_addc_u32 s25, s25, 0
	s_mov_b32 m0, s30
	s_nop 0
	global_load_lds_dwordx4 v128, s[24:25]
	s_mov_b32 m0, s31
	s_nop 0
	global_load_lds_dwordx4 v130, s[24:25]
	ds_read_b128 v[138:141], v132
	ds_read_b128 v[148:151], v132 offset:1024
	ds_read_b128 v[152:155], v132 offset:2048
	ds_read_b128 v[156:159], v132 offset:3072
	v_add_u32_e32 v132, s50, v144
	ds_read_b128 v[160:163], v132
	ds_read_b128 v[164:167], v132 offset:1024
	ds_read_b128 v[168:171], v132 offset:2048
	ds_read_b128 v[172:175], v132 offset:3072
	ds_read_b128 v[176:179], v147 offset:32768
	ds_read_b128 v[180:183], v147 offset:33792
	ds_read_b128 v[184:187], v147 offset:34816
	ds_read_b128 v[188:191], v147 offset:35840
	ds_read_b128 v[192:195], v147 offset:36864
	ds_read_b128 v[196:199], v147 offset:37888
	ds_read_b128 v[200:203], v147 offset:38912
	ds_read_b128 v[204:207], v147 offset:39936
	s_waitcnt vmcnt(8)
	s_waitcnt lgkmcnt(0)
	s_barrier
	s_setprio 1
	s_waitcnt lgkmcnt(0)
	v_mfma_f32_16x16x32_bf16 v[124:127], v[138:141], v[176:179], v[124:127]
	v_mfma_f32_16x16x32_bf16 v[120:123], v[152:155], v[176:179], v[120:123]
	v_mfma_f32_16x16x32_bf16 v[116:119], v[138:141], v[184:187], v[116:119]
	v_mfma_f32_16x16x32_bf16 v[104:107], v[152:155], v[184:187], v[104:107]
	v_mfma_f32_16x16x32_bf16 v[92:95], v[138:141], v[192:195], v[92:95]
	v_mfma_f32_16x16x32_bf16 v[88:91], v[152:155], v[192:195], v[88:91]
	v_mfma_f32_16x16x32_bf16 v[84:87], v[138:141], v[200:203], v[84:87]
	v_mfma_f32_16x16x32_bf16 v[72:75], v[152:155], v[200:203], v[72:75]
	v_mfma_f32_16x16x32_bf16 v[124:127], v[148:151], v[180:183], v[124:127]
	v_mfma_f32_16x16x32_bf16 v[120:123], v[156:159], v[180:183], v[120:123]
	v_mfma_f32_16x16x32_bf16 v[116:119], v[148:151], v[188:191], v[116:119]
	v_mfma_f32_16x16x32_bf16 v[104:107], v[156:159], v[188:191], v[104:107]
	v_mfma_f32_16x16x32_bf16 v[92:95], v[148:151], v[196:199], v[92:95]
	v_mfma_f32_16x16x32_bf16 v[88:91], v[156:159], v[196:199], v[88:91]
	v_mfma_f32_16x16x32_bf16 v[84:87], v[148:151], v[204:207], v[84:87]
	v_mfma_f32_16x16x32_bf16 v[72:75], v[156:159], v[204:207], v[72:75]
	s_setprio 0
	s_setprio 1
	v_mfma_f32_16x16x32_bf16 v[112:115], v[160:163], v[176:179], v[112:115]
	v_mfma_f32_16x16x32_bf16 v[108:111], v[168:171], v[176:179], v[108:111]
	v_mfma_f32_16x16x32_bf16 v[100:103], v[160:163], v[184:187], v[100:103]
	v_mfma_f32_16x16x32_bf16 v[96:99], v[168:171], v[184:187], v[96:99]
	v_mfma_f32_16x16x32_bf16 v[80:83], v[160:163], v[192:195], v[80:83]
	v_mfma_f32_16x16x32_bf16 v[76:79], v[168:171], v[192:195], v[76:79]
	v_mfma_f32_16x16x32_bf16 v[68:71], v[160:163], v[200:203], v[68:71]
	v_mfma_f32_16x16x32_bf16 v[64:67], v[168:171], v[200:203], v[64:67]
	v_mfma_f32_16x16x32_bf16 v[112:115], v[164:167], v[180:183], v[112:115]
	v_mfma_f32_16x16x32_bf16 v[108:111], v[172:175], v[180:183], v[108:111]
	v_mfma_f32_16x16x32_bf16 v[100:103], v[164:167], v[188:191], v[100:103]
	v_mfma_f32_16x16x32_bf16 v[96:99], v[172:175], v[188:191], v[96:99]
	v_mfma_f32_16x16x32_bf16 v[80:83], v[164:167], v[196:199], v[80:83]
	v_mfma_f32_16x16x32_bf16 v[76:79], v[172:175], v[196:199], v[76:79]
	v_mfma_f32_16x16x32_bf16 v[68:71], v[164:167], v[204:207], v[68:71]
	v_mfma_f32_16x16x32_bf16 v[64:67], v[172:175], v[204:207], v[64:67]
	s_setprio 0
	s_barrier
	s_add_u32 s24, s22, 0x8000
	s_addc_u32 s25, s23, 0
	s_add_i32 s49, s49, s3
	s_mov_b32 m0, s49
	s_nop 0
	global_load_lds_dwordx4 v128, s[24:25]
	s_add_i32 m0, s49, 0x2000
	s_add_u32 s22, s22, 0xc000
	s_addc_u32 s23, s23, 0
	global_load_lds_dwordx4 v130, s[24:25]
	s_add_i32 s24, s50, s3
	s_mov_b32 m0, s24
	s_nop 0
	global_load_lds_dwordx4 v128, s[22:23]
	s_add_i32 m0, s24, 0x2000
	s_nop 0
	global_load_lds_dwordx4 v130, s[22:23]
	s_mov_b32 m0, s36
	s_nop 0
	global_load_lds_dwordx4 v128, s[20:21]
	s_mov_b32 m0, s37
	s_nop 0
	global_load_lds_dwordx4 v130, s[20:21]
	ds_read_b128 v[176:179], v147 offset:49152
	ds_read_b128 v[180:183], v147 offset:50176
	ds_read_b128 v[184:187], v147 offset:51200
	ds_read_b128 v[188:191], v147 offset:52224
	ds_read_b128 v[192:195], v147 offset:53248
	ds_read_b128 v[196:199], v147 offset:54272
	ds_read_b128 v[200:203], v147 offset:55296
	ds_read_b128 v[204:207], v147 offset:56320
	s_waitcnt vmcnt(8)
	s_waitcnt lgkmcnt(0)
	s_barrier
	s_setprio 1
	s_waitcnt lgkmcnt(0)
	v_mfma_f32_16x16x32_bf16 v[60:63], v[138:141], v[176:179], v[60:63]
	v_mfma_f32_16x16x32_bf16 v[56:59], v[152:155], v[176:179], v[56:59]
	v_mfma_f32_16x16x32_bf16 v[48:51], v[138:141], v[184:187], v[48:51]
	v_mfma_f32_16x16x32_bf16 v[40:43], v[152:155], v[184:187], v[40:43]
	v_mfma_f32_16x16x32_bf16 v[28:31], v[138:141], v[192:195], v[28:31]
	v_mfma_f32_16x16x32_bf16 v[24:27], v[152:155], v[192:195], v[24:27]
	v_mfma_f32_16x16x32_bf16 v[16:19], v[138:141], v[200:203], v[16:19]
	v_mfma_f32_16x16x32_bf16 v[8:11], v[152:155], v[200:203], v[8:11]
	v_mfma_f32_16x16x32_bf16 v[60:63], v[148:151], v[180:183], v[60:63]
	v_mfma_f32_16x16x32_bf16 v[56:59], v[156:159], v[180:183], v[56:59]
	v_mfma_f32_16x16x32_bf16 v[48:51], v[148:151], v[188:191], v[48:51]
	v_mfma_f32_16x16x32_bf16 v[40:43], v[156:159], v[188:191], v[40:43]
	v_mfma_f32_16x16x32_bf16 v[28:31], v[148:151], v[196:199], v[28:31]
	v_mfma_f32_16x16x32_bf16 v[24:27], v[156:159], v[196:199], v[24:27]
	v_mfma_f32_16x16x32_bf16 v[16:19], v[148:151], v[204:207], v[16:19]
	v_mfma_f32_16x16x32_bf16 v[8:11], v[156:159], v[204:207], v[8:11]
	s_setprio 0
	s_setprio 1
	v_mfma_f32_16x16x32_bf16 v[52:55], v[160:163], v[176:179], v[52:55]
	v_mfma_f32_16x16x32_bf16 v[44:47], v[168:171], v[176:179], v[44:47]
	v_mfma_f32_16x16x32_bf16 v[36:39], v[160:163], v[184:187], v[36:39]
	v_mfma_f32_16x16x32_bf16 v[32:35], v[168:171], v[184:187], v[32:35]
	v_mfma_f32_16x16x32_bf16 v[20:23], v[160:163], v[192:195], v[20:23]
	v_mfma_f32_16x16x32_bf16 v[12:15], v[168:171], v[192:195], v[12:15]
	v_mfma_f32_16x16x32_bf16 v[4:7], v[160:163], v[200:203], v[4:7]
	v_mfma_f32_16x16x32_bf16 v[0:3], v[168:171], v[200:203], v[0:3]
	v_mfma_f32_16x16x32_bf16 v[52:55], v[164:167], v[180:183], v[52:55]
	v_mfma_f32_16x16x32_bf16 v[44:47], v[172:175], v[180:183], v[44:47]
	v_mfma_f32_16x16x32_bf16 v[36:39], v[164:167], v[188:191], v[36:39]
	v_mfma_f32_16x16x32_bf16 v[32:35], v[172:175], v[188:191], v[32:35]
	v_mfma_f32_16x16x32_bf16 v[20:23], v[164:167], v[196:199], v[20:23]
	v_mfma_f32_16x16x32_bf16 v[12:15], v[172:175], v[196:199], v[12:15]
	v_mfma_f32_16x16x32_bf16 v[4:7], v[164:167], v[204:207], v[4:7]
	v_mfma_f32_16x16x32_bf16 v[0:3], v[172:175], v[204:207], v[0:3]
	s_setprio 0
	s_barrier
	s_add_i32 s48, s48, 2
	s_add_u32 s18, s18, 0x10000
	s_addc_u32 s19, s19, 0
	s_add_u32 s46, s46, 0x10000
	s_addc_u32 s47, s47, 0
	s_cmp_gt_u32 s48, 61
	s_cbranch_scc0 .LBB0_716
	s_and_b64 vcc, exec, s[6:7]
	s_cbranch_vccz .LBB0_719
	s_barrier
